# cand2 + s_sleep 1 at the start of every K-loop load segment (load burst shifted away from the partner's first MFMAs)
# speedup vs baseline: 1.0027x; 1.0027x over previous
; #define PG8_STAGE(bufoff, gbase, voff) do { const char* gb_ = (const char*)(gbase); asm volatile("" : "+s"(gb_)); _Pragma("unroll") for (int _i = 0; _i < 2; ++_i) { unsigned vo_ = (voff)[_i]; asm volatile("" : "+v"(vo_));        \
;         __builtin_amdgcn_global_load_lds((const unsigned*)(gb_ + vo_), (PG8_LAS unsigned*)(lds + (bufoff) + ldsw + _i * 8192), 16, 0, 0); } } while (0)
; #define PG8_LDA(dst, b, h) do { _Pragma("unroll") for (int m = 0; m < 4; ++m) _Pragma("unroll") for (int k = 0; k < 2; ++k) dst[m][k] = *(const PG8_LAS bf16x8*)(lds + PG8_SA(b, h) + aoff + m * 2048 + k * 1024); } while (0)
; #define PG8_WAIT_V(n) asm volatile("s_waitcnt vmcnt(" #n ")" ::: "memory")
; #define PG8_WAIT_L(n) asm volatile("s_waitcnt lgkmcnt(" #n ")" ::: "memory")
; template <class Epi, class Sched, bool ALIGN_EPI = false, bool SP2 = false>
; __device__ __forceinline__ void gemm_phase(PG8_LAS unsigned char* lds, const Gemm g, const Sched& S, const Epi& E) {
;     ...
;             const bool last = (t == nt - 2);
;             const char* a1 = cA + (size_t)(t + 1) * kstep;
;             const char* a2 = last ? nA : cA + (size_t)(t + 2) * kstep; const char* b2 = last ? nB : cB + (size_t)(t + 2) * kstep;
;             const char* a3 = a2 + kstep; const char* b3 = b2 + kstep;
;             if (last && has_next) S.a_ready(nxt);
;             if constexpr (SP2) {
;             PG8_LDB(B0, 0, 0); PG8_LDB(B1, 0, 1); PG8_SCHED; PG8_LDA(At, 0, 0); PG8_STAGE(PG8_SA(1, 1), a1 + hstep, voffA);
;             PG8_WAIT_V(8); PG8_WAIT_L(0); PG8_BAR; PG8_MMA(0, 0, At, B0); PG8_MMA(0, 1, At, B1); PG8_BAR; PG8_SCHED;
;             PG8_LDA(At, 0, 1); PG8_STAGE(PG8_SB(0, 0), b2, voffB); PG8_STAGE(PG8_SB(0, 1), b2 + hstep, voffB); PG8_STAGE(PG8_SA(0, 0), a2, voffA);
;             PG8_WAIT_V(8); PG8_WAIT_L(0); PG8_BAR; PG8_MMA(1, 0, At, B0); PG8_MMA(1, 1, At, B1); PG8_BAR; PG8_SCHED;
;             PG8_LDB(B0, 1, 0); PG8_LDB(B1, 1, 1); PG8_SCHED; PG8_LDA(At, 1, 0); PG8_STAGE(PG8_SA(0, 1), a2 + hstep, voffA);
;             PG8_WAIT_V(8); PG8_WAIT_L(0); PG8_BAR; PG8_MMA(0, 0, At, B0); PG8_MMA(0, 1, At, B1); PG8_BAR; PG8_SCHED;
;             PG8_LDA(At, 1, 1); PG8_STAGE(PG8_SB(1, 0), b3, voffB); PG8_STAGE(PG8_SB(1, 1), b3 + hstep, voffB); PG8_STAGE(PG8_SA(1, 0), a3, voffA);
;             PG8_WAIT_V(8); PG8_WAIT_L(0); PG8_BAR; PG8_MMA(1, 0, At, B0); PG8_MMA(1, 1, At, B1); PG8_BAR; PG8_SCHED;
.LBB0_232:
	s_add_u32 s2, s0, 0x100
	s_addc_u32 s3, s1, 0
	s_cmp_eq_u32 s30, 28
	s_cselect_b32 s10, s25, s2
	s_cselect_b32 s11, s24, s3
	s_cselect_b32 s8, s27, s28
	s_cselect_b32 s9, s26, s29
	s_add_u32 s6, s10, 0x80
	s_addc_u32 s7, s11, 0
	s_add_i32 s31, 0, 0x10000
	s_add_i32 s33, 0, 0x14000
	ds_read_b128 v[66:69], v244
	ds_read_b128 v[70:73], v244 offset:1024
	ds_read_b128 v[74:77], v244 offset:2048
	ds_read_b128 v[78:81], v244 offset:3072
	ds_read_b128 v[146:149], v244 offset:16384
	ds_read_b128 v[150:153], v244 offset:17408
	ds_read_b128 v[154:157], v244 offset:18432
	ds_read_b128 v[158:161], v244 offset:19456
	s_add_u32 s0, s0, 0x80080
	s_addc_u32 s1, s1, 0
	ds_read_b128 v[178:181], v223
	ds_read_b128 v[182:185], v223 offset:1024
	ds_read_b128 v[192:195], v223 offset:2048
	ds_read_b128 v[196:199], v223 offset:3072
	ds_read_b128 v[200:203], v223 offset:4096
	ds_read_b128 v[204:207], v223 offset:5120
	ds_read_b128 v[208:211], v223 offset:6144
	ds_read_b128 v[212:215], v223 offset:7168
	s_add_i32 m0, s13, 0xc000
	s_nop 0
	global_load_lds_dwordx4 v1, s[0:1]
	s_add_i32 m0, s13, 0xe000
	s_nop 0
	global_load_lds_dwordx4 v191, s[0:1]
	s_waitcnt vmcnt(8)
	s_waitcnt lgkmcnt(0)
	s_barrier
	s_setprio 1
	s_waitcnt lgkmcnt(0)
	v_mfma_f32_16x16x32_bf16 v[142:145], v[66:69], v[178:181], v[142:145]
	v_mfma_f32_16x16x32_bf16 v[142:145], v[70:73], v[182:185], v[142:145]
	v_mfma_f32_16x16x32_bf16 v[134:137], v[66:69], v[192:195], v[134:137]
	v_mfma_f32_16x16x32_bf16 v[134:137], v[70:73], v[196:199], v[134:137]
	v_mfma_f32_16x16x32_bf16 v[126:129], v[66:69], v[200:203], v[126:129]
	v_mfma_f32_16x16x32_bf16 v[126:129], v[70:73], v[204:207], v[126:129]
	v_mfma_f32_16x16x32_bf16 v[118:121], v[66:69], v[208:211], v[118:121]
	v_mfma_f32_16x16x32_bf16 v[118:121], v[70:73], v[212:215], v[118:121]
	v_mfma_f32_16x16x32_bf16 v[138:141], v[74:77], v[178:181], v[138:141]
	v_mfma_f32_16x16x32_bf16 v[138:141], v[78:81], v[182:185], v[138:141]
	v_mfma_f32_16x16x32_bf16 v[130:133], v[74:77], v[192:195], v[130:133]
	v_mfma_f32_16x16x32_bf16 v[130:133], v[78:81], v[196:199], v[130:133]
	v_mfma_f32_16x16x32_bf16 v[122:125], v[74:77], v[200:203], v[122:125]
	v_mfma_f32_16x16x32_bf16 v[122:125], v[78:81], v[204:207], v[122:125]
	v_mfma_f32_16x16x32_bf16 v[114:117], v[74:77], v[208:211], v[114:117]
	v_mfma_f32_16x16x32_bf16 v[114:117], v[78:81], v[212:215], v[114:117]
	s_setprio 0
	s_setprio 1
	v_mfma_f32_16x16x32_bf16 v[62:65], v[146:149], v[178:181], v[62:65]
	v_mfma_f32_16x16x32_bf16 v[62:65], v[150:153], v[182:185], v[62:65]
	v_mfma_f32_16x16x32_bf16 v[54:57], v[146:149], v[192:195], v[54:57]
	v_mfma_f32_16x16x32_bf16 v[54:57], v[150:153], v[196:199], v[54:57]
	v_mfma_f32_16x16x32_bf16 v[46:49], v[146:149], v[200:203], v[46:49]
	v_mfma_f32_16x16x32_bf16 v[46:49], v[150:153], v[204:207], v[46:49]
	v_mfma_f32_16x16x32_bf16 v[38:41], v[146:149], v[208:211], v[38:41]
	v_mfma_f32_16x16x32_bf16 v[38:41], v[150:153], v[212:215], v[38:41]
	v_mfma_f32_16x16x32_bf16 v[58:61], v[154:157], v[178:181], v[58:61]
	v_mfma_f32_16x16x32_bf16 v[58:61], v[158:161], v[182:185], v[58:61]
	v_mfma_f32_16x16x32_bf16 v[50:53], v[154:157], v[192:195], v[50:53]
	v_mfma_f32_16x16x32_bf16 v[50:53], v[158:161], v[196:199], v[50:53]
	v_mfma_f32_16x16x32_bf16 v[42:45], v[154:157], v[200:203], v[42:45]
	v_mfma_f32_16x16x32_bf16 v[42:45], v[158:161], v[204:207], v[42:45]
	v_mfma_f32_16x16x32_bf16 v[34:37], v[154:157], v[208:211], v[34:37]
	v_mfma_f32_16x16x32_bf16 v[34:37], v[158:161], v[212:215], v[34:37]
	s_setprio 0
	s_barrier
	s_sleep 1
	s_mov_b64 s[0:1], s[8:9]
	s_add_i32 s31, s31, s12
	ds_read_b128 v[178:181], v223 offset:16384
	ds_read_b128 v[182:185], v223 offset:17408
	ds_read_b128 v[192:195], v223 offset:18432
	ds_read_b128 v[196:199], v223 offset:19456
	ds_read_b128 v[200:203], v223 offset:20480
	ds_read_b128 v[204:207], v223 offset:21504
	ds_read_b128 v[208:211], v223 offset:22528
	ds_read_b128 v[212:215], v223 offset:23552
	s_mov_b32 m0, s31
	s_nop 0
	global_load_lds_dwordx4 v189, s[0:1]
	s_add_i32 m0, s31, 0x2000
	s_nop 0
	global_load_lds_dwordx4 v219, s[0:1]
	s_add_u32 s0, s8, 0x80000
	s_addc_u32 s1, s9, 0
	s_add_i32 s31, s33, s12
	s_mov_b32 m0, s31
	s_nop 0
	global_load_lds_dwordx4 v189, s[0:1]
	s_add_i32 m0, s31, 0x2000
	s_nop 0
	global_load_lds_dwordx4 v219, s[0:1]
	s_mov_b64 s[0:1], s[10:11]
	s_mov_b32 m0, s13
	s_nop 0
	global_load_lds_dwordx4 v1, s[0:1]
	s_mov_b32 m0, s14
	s_nop 0
	global_load_lds_dwordx4 v191, s[0:1]
	s_waitcnt vmcnt(8)
	s_waitcnt lgkmcnt(0)
	s_barrier
; #define PG8_STAGE(bufoff, gbase, voff) do { const char* gb_ = (const char*)(gbase); asm volatile("" : "+s"(gb_)); _Pragma("unroll") for (int _i = 0; _i < 2; ++_i) { unsigned vo_ = (voff)[_i]; asm volatile("" : "+v"(vo_));        \
;         __builtin_amdgcn_global_load_lds((const unsigned*)(gb_ + vo_), (PG8_LAS unsigned*)(lds + (bufoff) + ldsw + _i * 8192), 16, 0, 0); } } while (0)
; #define PG8_LDA(dst, b, h) do { _Pragma("unroll") for (int m = 0; m < 4; ++m) _Pragma("unroll") for (int k = 0; k < 2; ++k) dst[m][k] = *(const PG8_LAS bf16x8*)(lds + PG8_SA(b, h) + aoff + m * 2048 + k * 1024); } while (0)
; #define PG8_LDB(dst, b, h) do { _Pragma("unroll") for (int n = 0; n < 2; ++n) _Pragma("unroll") for (int k = 0; k < 2; ++k) dst[n][k] = *(const PG8_LAS bf16x8*)(lds + PG8_SB(b, h) + boff + n * 2048 + k * 1024); } while (0)
; #define PG8_MMA(ai, bj, At, Bt) do { __builtin_amdgcn_s_setprio(1); _Pragma("unroll") for (int m = 0; m < 4; ++m) _Pragma("unroll") for (int n = 0; n < 2; ++n) _Pragma("unroll") for (int k = 0; k < 2; ++k) \
;         acc[ai][bj][m][n] = __builtin_amdgcn_mfma_f32_16x16x32_bf16(Bt[n][k], At[m][k], acc[ai][bj][m][n], 0, 0, 0); __builtin_amdgcn_s_setprio(0); } while (0)
; #define PG8_WAIT_V(n) asm volatile("s_waitcnt vmcnt(" #n ")" ::: "memory")
; #define PG8_WAIT_L(n) asm volatile("s_waitcnt lgkmcnt(" #n ")" ::: "memory")
; #define PG8_BAR __builtin_amdgcn_s_barrier()
; #define PG8_SCHED __builtin_amdgcn_sched_barrier(0)
; template <class Epi, class Sched, bool ALIGN_EPI = false, bool SP2 = false>
; __device__ __forceinline__ void gemm_phase(PG8_LAS unsigned char* lds, const Gemm g, const Sched& S, const Epi& E) {
;     ...
;             PG8_WAIT_V(8); PG8_WAIT_L(0); PG8_BAR; PG8_MMA(0, 0, At, B0); PG8_MMA(0, 1, At, B1); PG8_BAR; PG8_SCHED;
;             PG8_LDA(At, 0, 1); PG8_STAGE(PG8_SB(0, 0), b2, voffB); PG8_STAGE(PG8_SB(0, 1), b2 + hstep, voffB); PG8_STAGE(PG8_SA(0, 0), a2, voffA);
;             PG8_WAIT_V(8); PG8_WAIT_L(0); PG8_BAR; PG8_MMA(1, 0, At, B0); PG8_MMA(1, 1, At, B1); PG8_BAR; PG8_SCHED;
;             PG8_LDB(B0, 1, 0); PG8_LDB(B1, 1, 1); PG8_SCHED; PG8_LDA(At, 1, 0); PG8_STAGE(PG8_SA(0, 1), a2 + hstep, voffA);
;             PG8_WAIT_V(8); PG8_WAIT_L(0); PG8_BAR; PG8_MMA(0, 0, At, B0); PG8_MMA(0, 1, At, B1); PG8_BAR; PG8_SCHED;
	s_setprio 1
	s_waitcnt lgkmcnt(0)
	v_mfma_f32_16x16x32_bf16 v[110:113], v[66:69], v[178:181], v[110:113]
	v_mfma_f32_16x16x32_bf16 v[110:113], v[70:73], v[182:185], v[110:113]
	v_mfma_f32_16x16x32_bf16 v[102:105], v[66:69], v[192:195], v[102:105]
	v_mfma_f32_16x16x32_bf16 v[102:105], v[70:73], v[196:199], v[102:105]
	v_mfma_f32_16x16x32_bf16 v[94:97], v[66:69], v[200:203], v[94:97]
	v_mfma_f32_16x16x32_bf16 v[94:97], v[70:73], v[204:207], v[94:97]
	v_mfma_f32_16x16x32_bf16 v[66:69], v[66:69], v[208:211], v[86:89]
	v_mfma_f32_16x16x32_bf16 v[66:69], v[70:73], v[212:215], v[66:69]
	v_mfma_f32_16x16x32_bf16 v[106:109], v[74:77], v[178:181], v[106:109]
	v_mfma_f32_16x16x32_bf16 v[106:109], v[78:81], v[182:185], v[106:109]
	v_mfma_f32_16x16x32_bf16 v[98:101], v[74:77], v[192:195], v[98:101]
	v_mfma_f32_16x16x32_bf16 v[98:101], v[78:81], v[196:199], v[98:101]
	v_mfma_f32_16x16x32_bf16 v[90:93], v[74:77], v[200:203], v[90:93]
	v_mfma_f32_16x16x32_bf16 v[90:93], v[78:81], v[204:207], v[90:93]
	v_mfma_f32_16x16x32_bf16 v[70:73], v[74:77], v[208:211], v[82:85]
	v_mfma_f32_16x16x32_bf16 v[70:73], v[78:81], v[212:215], v[70:73]
	s_setprio 0
	s_setprio 1
	v_mfma_f32_16x16x32_bf16 v[30:33], v[146:149], v[178:181], v[30:33]
	v_mfma_f32_16x16x32_bf16 v[30:33], v[150:153], v[182:185], v[30:33]
	v_mfma_f32_16x16x32_bf16 v[22:25], v[146:149], v[192:195], v[22:25]
	v_mfma_f32_16x16x32_bf16 v[22:25], v[150:153], v[196:199], v[22:25]
	v_mfma_f32_16x16x32_bf16 v[14:17], v[146:149], v[200:203], v[14:17]
	v_mfma_f32_16x16x32_bf16 v[14:17], v[150:153], v[204:207], v[14:17]
	v_mfma_f32_16x16x32_bf16 v[6:9], v[146:149], v[208:211], v[6:9]
	v_mfma_f32_16x16x32_bf16 v[6:9], v[150:153], v[212:215], v[6:9]
	v_mfma_f32_16x16x32_bf16 v[26:29], v[154:157], v[178:181], v[26:29]
	v_mfma_f32_16x16x32_bf16 v[26:29], v[158:161], v[182:185], v[26:29]
	v_mfma_f32_16x16x32_bf16 v[18:21], v[154:157], v[192:195], v[18:21]
	v_mfma_f32_16x16x32_bf16 v[18:21], v[158:161], v[196:199], v[18:21]
	v_mfma_f32_16x16x32_bf16 v[10:13], v[154:157], v[200:203], v[10:13]
	v_mfma_f32_16x16x32_bf16 v[10:13], v[158:161], v[204:207], v[10:13]
	v_mfma_f32_16x16x32_bf16 v[2:5], v[154:157], v[208:211], v[2:5]
	v_mfma_f32_16x16x32_bf16 v[2:5], v[158:161], v[212:215], v[2:5]
	s_setprio 0
	s_barrier
	s_sleep 1
	s_add_i32 s31, 0, 0x18000
	s_add_i32 s33, 0, 0x1c000
	ds_read_b128 v[74:77], v244 offset:32768
	ds_read_b128 v[78:81], v244 offset:33792
	ds_read_b128 v[82:85], v244 offset:34816
	ds_read_b128 v[146:149], v244 offset:35840
	ds_read_b128 v[150:153], v244 offset:49152
	ds_read_b128 v[154:157], v244 offset:50176
	ds_read_b128 v[158:161], v244 offset:51200
	ds_read_b128 v[178:181], v244 offset:52224
	s_add_u32 s0, s10, 0x80000
	s_addc_u32 s1, s11, 0
	s_mov_b32 m0, s15
	ds_read_b128 v[86:89], v223 offset:32768
	ds_read_b128 v[182:185], v223 offset:33792
	ds_read_b128 v[192:195], v223 offset:34816
	ds_read_b128 v[196:199], v223 offset:35840
	ds_read_b128 v[200:203], v223 offset:36864
	ds_read_b128 v[204:207], v223 offset:37888
	ds_read_b128 v[208:211], v223 offset:38912
	ds_read_b128 v[212:215], v223 offset:39936
	s_nop 0
	global_load_lds_dwordx4 v1, s[0:1]
	s_mov_b32 m0, s16
	s_nop 0
	global_load_lds_dwordx4 v191, s[0:1]
	s_waitcnt vmcnt(8)
	s_waitcnt lgkmcnt(0)
	s_barrier
	s_setprio 1
	s_waitcnt lgkmcnt(0)
	v_mfma_f32_16x16x32_bf16 v[142:145], v[74:77], v[86:89], v[142:145]
	v_mfma_f32_16x16x32_bf16 v[142:145], v[78:81], v[182:185], v[142:145]
	v_mfma_f32_16x16x32_bf16 v[134:137], v[74:77], v[192:195], v[134:137]
	v_mfma_f32_16x16x32_bf16 v[134:137], v[78:81], v[196:199], v[134:137]
	v_mfma_f32_16x16x32_bf16 v[126:129], v[74:77], v[200:203], v[126:129]
	v_mfma_f32_16x16x32_bf16 v[126:129], v[78:81], v[204:207], v[126:129]
	v_mfma_f32_16x16x32_bf16 v[118:121], v[74:77], v[208:211], v[118:121]
	v_mfma_f32_16x16x32_bf16 v[118:121], v[78:81], v[212:215], v[118:121]
	v_mfma_f32_16x16x32_bf16 v[138:141], v[82:85], v[86:89], v[138:141]
	v_mfma_f32_16x16x32_bf16 v[138:141], v[146:149], v[182:185], v[138:141]
	v_mfma_f32_16x16x32_bf16 v[130:133], v[82:85], v[192:195], v[130:133]
	v_mfma_f32_16x16x32_bf16 v[130:133], v[146:149], v[196:199], v[130:133]
	v_mfma_f32_16x16x32_bf16 v[122:125], v[82:85], v[200:203], v[122:125]
	v_mfma_f32_16x16x32_bf16 v[122:125], v[146:149], v[204:207], v[122:125]
	v_mfma_f32_16x16x32_bf16 v[114:117], v[82:85], v[208:211], v[114:117]
	v_mfma_f32_16x16x32_bf16 v[114:117], v[146:149], v[212:215], v[114:117]
	s_setprio 0
	s_setprio 1
	v_mfma_f32_16x16x32_bf16 v[62:65], v[150:153], v[86:89], v[62:65]
	v_mfma_f32_16x16x32_bf16 v[62:65], v[154:157], v[182:185], v[62:65]
	v_mfma_f32_16x16x32_bf16 v[54:57], v[150:153], v[192:195], v[54:57]
	v_mfma_f32_16x16x32_bf16 v[54:57], v[154:157], v[196:199], v[54:57]
	v_mfma_f32_16x16x32_bf16 v[46:49], v[150:153], v[200:203], v[46:49]
	v_mfma_f32_16x16x32_bf16 v[46:49], v[154:157], v[204:207], v[46:49]
	v_mfma_f32_16x16x32_bf16 v[38:41], v[150:153], v[208:211], v[38:41]
	v_mfma_f32_16x16x32_bf16 v[38:41], v[154:157], v[212:215], v[38:41]
	v_mfma_f32_16x16x32_bf16 v[58:61], v[158:161], v[86:89], v[58:61]
	v_mfma_f32_16x16x32_bf16 v[58:61], v[178:181], v[182:185], v[58:61]
	v_mfma_f32_16x16x32_bf16 v[50:53], v[158:161], v[192:195], v[50:53]
	v_mfma_f32_16x16x32_bf16 v[50:53], v[178:181], v[196:199], v[50:53]
	v_mfma_f32_16x16x32_bf16 v[42:45], v[158:161], v[200:203], v[42:45]
	v_mfma_f32_16x16x32_bf16 v[42:45], v[178:181], v[204:207], v[42:45]
	v_mfma_f32_16x16x32_bf16 v[34:37], v[158:161], v[208:211], v[34:37]
	v_mfma_f32_16x16x32_bf16 v[34:37], v[178:181], v[212:215], v[34:37]
	s_setprio 0
	s_barrier
; #define PG8_STAGE(bufoff, gbase, voff) do { const char* gb_ = (const char*)(gbase); asm volatile("" : "+s"(gb_)); _Pragma("unroll") for (int _i = 0; _i < 2; ++_i) { unsigned vo_ = (voff)[_i]; asm volatile("" : "+v"(vo_));        \
;         __builtin_amdgcn_global_load_lds((const unsigned*)(gb_ + vo_), (PG8_LAS unsigned*)(lds + (bufoff) + ldsw + _i * 8192), 16, 0, 0); } } while (0)
; #define PG8_LDA(dst, b, h) do { _Pragma("unroll") for (int m = 0; m < 4; ++m) _Pragma("unroll") for (int k = 0; k < 2; ++k) dst[m][k] = *(const PG8_LAS bf16x8*)(lds + PG8_SA(b, h) + aoff + m * 2048 + k * 1024); } while (0)
; #define PG8_LDB(dst, b, h) do { _Pragma("unroll") for (int n = 0; n < 2; ++n) _Pragma("unroll") for (int k = 0; k < 2; ++k) dst[n][k] = *(const PG8_LAS bf16x8*)(lds + PG8_SB(b, h) + boff + n * 2048 + k * 1024); } while (0)
; #define PG8_MMA(ai, bj, At, Bt) do { __builtin_amdgcn_s_setprio(1); _Pragma("unroll") for (int m = 0; m < 4; ++m) _Pragma("unroll") for (int n = 0; n < 2; ++n) _Pragma("unroll") for (int k = 0; k < 2; ++k) \
;         acc[ai][bj][m][n] = __builtin_amdgcn_mfma_f32_16x16x32_bf16(Bt[n][k], At[m][k], acc[ai][bj][m][n], 0, 0, 0); __builtin_amdgcn_s_setprio(0); } while (0)
; #define PG8_WAIT_V(n) asm volatile("s_waitcnt vmcnt(" #n ")" ::: "memory")
; #define PG8_WAIT_L(n) asm volatile("s_waitcnt lgkmcnt(" #n ")" ::: "memory")
; #define PG8_BAR __builtin_amdgcn_s_barrier()
; #define PG8_SCHED __builtin_amdgcn_sched_barrier(0)
; template <class Epi, class Sched, bool ALIGN_EPI = false, bool SP2 = false>
; __device__ __forceinline__ void gemm_phase(PG8_LAS unsigned char* lds, const Gemm g, const Sched& S, const Epi& E) {
;     ...
;             PG8_LDB(B0, 1, 0); PG8_LDB(B1, 1, 1); PG8_SCHED; PG8_LDA(At, 1, 0); PG8_STAGE(PG8_SA(0, 1), a2 + hstep, voffA);
;             PG8_WAIT_V(8); PG8_WAIT_L(0); PG8_BAR; PG8_MMA(0, 0, At, B0); PG8_MMA(0, 1, At, B1); PG8_BAR; PG8_SCHED;
;             PG8_LDA(At, 1, 1); PG8_STAGE(PG8_SB(1, 0), b3, voffB); PG8_STAGE(PG8_SB(1, 1), b3 + hstep, voffB); PG8_STAGE(PG8_SA(1, 0), a3, voffA);
;             PG8_WAIT_V(8); PG8_WAIT_L(0); PG8_BAR; PG8_MMA(1, 0, At, B0); PG8_MMA(1, 1, At, B1); PG8_BAR; PG8_SCHED;
;     ...
;         if constexpr (ALIGN_EPI) { if (wr == 0) PG8_BAR; }
	s_sleep 1
	s_add_u32 s0, s8, 0x80
	s_addc_u32 s1, s9, 0
	s_add_i32 s10, s31, s12
	ds_read_b128 v[182:185], v223 offset:49152
	ds_read_b128 v[192:195], v223 offset:50176
	ds_read_b128 v[196:199], v223 offset:51200
	ds_read_b128 v[200:203], v223 offset:52224
	ds_read_b128 v[204:207], v223 offset:53248
	ds_read_b128 v[208:211], v223 offset:54272
	ds_read_b128 v[212:215], v223 offset:55296
	ds_read_b128 v[224:227], v223 offset:56320
	s_mov_b32 m0, s10
	s_nop 0
	global_load_lds_dwordx4 v189, s[0:1]
	s_add_i32 m0, s10, 0x2000
	s_nop 0
	global_load_lds_dwordx4 v219, s[0:1]
	s_add_u32 s0, s8, 0x80080
	s_addc_u32 s1, s9, 0
	s_add_i32 s8, s33, s12
	s_mov_b32 m0, s8
	s_nop 0
	global_load_lds_dwordx4 v189, s[0:1]
	s_add_i32 m0, s8, 0x2000
	s_nop 0
	global_load_lds_dwordx4 v219, s[0:1]
	s_mov_b32 m0, s19
	s_nop 0
	global_load_lds_dwordx4 v1, s[6:7]
	s_mov_b32 m0, s20
	s_nop 0
	global_load_lds_dwordx4 v191, s[6:7]
	s_waitcnt vmcnt(8)
	s_waitcnt lgkmcnt(0)
	s_barrier
	s_setprio 1
	s_waitcnt lgkmcnt(0)
	v_mfma_f32_16x16x32_bf16 v[86:89], v[74:77], v[182:185], v[110:113]
	v_mfma_f32_16x16x32_bf16 v[110:113], v[78:81], v[192:195], v[86:89]
	v_mfma_f32_16x16x32_bf16 v[66:69], v[74:77], v[212:215], v[66:69]
	v_mfma_f32_16x16x32_bf16 v[86:89], v[82:85], v[182:185], v[106:109]
	v_mfma_f32_16x16x32_bf16 v[106:109], v[146:149], v[192:195], v[86:89]
	v_mfma_f32_16x16x32_bf16 v[86:89], v[74:77], v[196:199], v[102:105]
	v_mfma_f32_16x16x32_bf16 v[102:105], v[78:81], v[200:203], v[86:89]
	v_mfma_f32_16x16x32_bf16 v[86:89], v[82:85], v[196:199], v[98:101]
	v_mfma_f32_16x16x32_bf16 v[98:101], v[146:149], v[200:203], v[86:89]
	v_mfma_f32_16x16x32_bf16 v[86:89], v[74:77], v[204:207], v[94:97]
	v_mfma_f32_16x16x32_bf16 v[94:97], v[78:81], v[208:211], v[86:89]
	v_mfma_f32_16x16x32_bf16 v[86:89], v[82:85], v[204:207], v[90:93]
	v_mfma_f32_16x16x32_bf16 v[90:93], v[146:149], v[208:211], v[86:89]
	v_mfma_f32_16x16x32_bf16 v[86:89], v[78:81], v[224:227], v[66:69]
	v_mfma_f32_16x16x32_bf16 v[66:69], v[82:85], v[212:215], v[70:73]
	v_mfma_f32_16x16x32_bf16 v[82:85], v[146:149], v[224:227], v[66:69]
	s_setprio 0
	s_setprio 1
	v_mfma_f32_16x16x32_bf16 v[30:33], v[150:153], v[182:185], v[30:33]
	v_mfma_f32_16x16x32_bf16 v[30:33], v[154:157], v[192:195], v[30:33]
	v_mfma_f32_16x16x32_bf16 v[22:25], v[150:153], v[196:199], v[22:25]
	v_mfma_f32_16x16x32_bf16 v[22:25], v[154:157], v[200:203], v[22:25]
	v_mfma_f32_16x16x32_bf16 v[14:17], v[150:153], v[204:207], v[14:17]
	v_mfma_f32_16x16x32_bf16 v[14:17], v[154:157], v[208:211], v[14:17]
	v_mfma_f32_16x16x32_bf16 v[6:9], v[150:153], v[212:215], v[6:9]
	v_mfma_f32_16x16x32_bf16 v[6:9], v[154:157], v[224:227], v[6:9]
	v_mfma_f32_16x16x32_bf16 v[26:29], v[158:161], v[182:185], v[26:29]
	v_mfma_f32_16x16x32_bf16 v[26:29], v[178:181], v[192:195], v[26:29]
	v_mfma_f32_16x16x32_bf16 v[18:21], v[158:161], v[196:199], v[18:21]
	v_mfma_f32_16x16x32_bf16 v[18:21], v[178:181], v[200:203], v[18:21]
	v_mfma_f32_16x16x32_bf16 v[10:13], v[158:161], v[204:207], v[10:13]
	v_mfma_f32_16x16x32_bf16 v[10:13], v[178:181], v[208:211], v[10:13]
	v_mfma_f32_16x16x32_bf16 v[2:5], v[158:161], v[212:215], v[2:5]
	v_mfma_f32_16x16x32_bf16 v[2:5], v[178:181], v[224:227], v[2:5]
	s_setprio 0
	s_barrier
	s_sleep 1
	s_add_i32 s30, s30, 2
	s_add_u32 s28, s28, 0x100
	s_addc_u32 s29, s29, 0
	s_cmp_gt_u32 s30, 29
	s_mov_b64 s[0:1], s[2:3]
	s_cbranch_scc0 .LBB0_232
	s_and_b64 vcc, exec, s[44:45]
	s_cbranch_vccz .LBB0_235
	s_barrier

; #define PG8_STAGE(bufoff, gbase, voff) do { const char* gb_ = (const char*)(gbase); asm volatile("" : "+s"(gb_)); _Pragma("unroll") for (int _i = 0; _i < 2; ++_i) { unsigned vo_ = (voff)[_i]; asm volatile("" : "+v"(vo_));        \
;         __builtin_amdgcn_global_load_lds((const unsigned*)(gb_ + vo_), (PG8_LAS unsigned*)(lds + (bufoff) + ldsw + _i * 8192), 16, 0, 0); } } while (0)
; #define PG8_LDA(dst, b, h) do { _Pragma("unroll") for (int m = 0; m < 4; ++m) _Pragma("unroll") for (int k = 0; k < 2; ++k) dst[m][k] = *(const PG8_LAS bf16x8*)(lds + PG8_SA(b, h) + aoff + m * 2048 + k * 1024); } while (0)
; #define PG8_WAIT_V(n) asm volatile("s_waitcnt vmcnt(" #n ")" ::: "memory")
; #define PG8_WAIT_L(n) asm volatile("s_waitcnt lgkmcnt(" #n ")" ::: "memory")
; template <class Epi, class Sched, bool ALIGN_EPI = false, bool SP2 = false>
; __device__ __forceinline__ void gemm_phase(PG8_LAS unsigned char* lds, const Gemm g, const Sched& S, const Epi& E) {
;     ...
;             const bool last = (t == nt - 2);
;             const char* a1 = cA + (size_t)(t + 1) * kstep;
;             const char* a2 = last ? nA : cA + (size_t)(t + 2) * kstep; const char* b2 = last ? nB : cB + (size_t)(t + 2) * kstep;
;             const char* a3 = a2 + kstep; const char* b3 = b2 + kstep;
;             if (last && has_next) S.a_ready(nxt);
;             if constexpr (SP2) {
;             PG8_LDB(B0, 0, 0); PG8_LDB(B1, 0, 1); PG8_SCHED; PG8_LDA(At, 0, 0); PG8_STAGE(PG8_SA(1, 1), a1 + hstep, voffA);
;             PG8_WAIT_V(8); PG8_WAIT_L(0); PG8_BAR; PG8_MMA(0, 0, At, B0); PG8_MMA(0, 1, At, B1); PG8_BAR; PG8_SCHED;
;             PG8_LDA(At, 0, 1); PG8_STAGE(PG8_SB(0, 0), b2, voffB); PG8_STAGE(PG8_SB(0, 1), b2 + hstep, voffB); PG8_STAGE(PG8_SA(0, 0), a2, voffA);
;             PG8_WAIT_V(8); PG8_WAIT_L(0); PG8_BAR; PG8_MMA(1, 0, At, B0); PG8_MMA(1, 1, At, B1); PG8_BAR; PG8_SCHED;
;             PG8_LDB(B0, 1, 0); PG8_LDB(B1, 1, 1); PG8_SCHED; PG8_LDA(At, 1, 0); PG8_STAGE(PG8_SA(0, 1), a2 + hstep, voffA);
;             PG8_WAIT_V(8); PG8_WAIT_L(0); PG8_BAR; PG8_MMA(0, 0, At, B0); PG8_MMA(0, 1, At, B1); PG8_BAR; PG8_SCHED;
;             PG8_LDA(At, 1, 1); PG8_STAGE(PG8_SB(1, 0), b3, voffB); PG8_STAGE(PG8_SB(1, 1), b3 + hstep, voffB); PG8_STAGE(PG8_SA(1, 0), a3, voffA);
;             PG8_WAIT_V(8); PG8_WAIT_L(0); PG8_BAR; PG8_MMA(1, 0, At, B0); PG8_MMA(1, 1, At, B1); PG8_BAR; PG8_SCHED;
.LBB0_555:
	s_add_u32 s6, s4, 0x100
	s_addc_u32 s7, s5, 0
	s_cmp_eq_u32 s51, 28
	s_cselect_b32 s12, s35, s6
	s_cselect_b32 s13, s34, s7
	s_cselect_b32 s10, s39, s40
	s_cselect_b32 s11, s38, s49
	s_add_u32 s8, s12, 0x80
	s_addc_u32 s9, s13, 0
	s_add_i32 s56, 0, 0x10000
	s_add_i32 s57, 0, 0x14000
	ds_read_b128 v[26:29], v244
	ds_read_b128 v[30:33], v244 offset:1024
	ds_read_b128 v[98:101], v244 offset:2048
	ds_read_b128 v[102:105], v244 offset:3072
	ds_read_b128 v[146:149], v244 offset:16384
	ds_read_b128 v[150:153], v244 offset:17408
	ds_read_b128 v[154:157], v244 offset:18432
	ds_read_b128 v[158:161], v244 offset:19456
	s_add_u32 s4, s4, 0x80080
	s_addc_u32 s5, s5, 0
	ds_read_b128 v[178:181], v210
	ds_read_b128 v[182:185], v210 offset:1024
	ds_read_b128 v[186:189], v210 offset:2048
	ds_read_b128 v[190:193], v210 offset:3072
	ds_read_b128 v[194:197], v210 offset:4096
	ds_read_b128 v[198:201], v210 offset:5120
	ds_read_b128 v[202:205], v210 offset:6144
	ds_read_b128 v[212:215], v210 offset:7168
	s_add_i32 m0, s18, 0xc000
	s_nop 0
	global_load_lds_dwordx4 v1, s[4:5]
	s_add_i32 m0, s18, 0xe000
	s_nop 0
	global_load_lds_dwordx4 v164, s[4:5]
	s_waitcnt vmcnt(8)
	s_waitcnt lgkmcnt(0)
	s_barrier
	s_setprio 1
	s_waitcnt lgkmcnt(0)
	v_mfma_f32_16x16x32_bf16 v[142:145], v[26:29], v[178:181], v[142:145]
	v_mfma_f32_16x16x32_bf16 v[142:145], v[30:33], v[182:185], v[142:145]
	v_mfma_f32_16x16x32_bf16 v[134:137], v[26:29], v[186:189], v[134:137]
	v_mfma_f32_16x16x32_bf16 v[134:137], v[30:33], v[190:193], v[134:137]
	v_mfma_f32_16x16x32_bf16 v[126:129], v[26:29], v[194:197], v[126:129]
	v_mfma_f32_16x16x32_bf16 v[126:129], v[30:33], v[198:201], v[126:129]
	v_mfma_f32_16x16x32_bf16 v[118:121], v[26:29], v[202:205], v[118:121]
	v_mfma_f32_16x16x32_bf16 v[118:121], v[30:33], v[212:215], v[118:121]
	v_mfma_f32_16x16x32_bf16 v[138:141], v[98:101], v[178:181], v[138:141]
	v_mfma_f32_16x16x32_bf16 v[138:141], v[102:105], v[182:185], v[138:141]
	v_mfma_f32_16x16x32_bf16 v[130:133], v[98:101], v[186:189], v[130:133]
	v_mfma_f32_16x16x32_bf16 v[130:133], v[102:105], v[190:193], v[130:133]
	v_mfma_f32_16x16x32_bf16 v[122:125], v[98:101], v[194:197], v[122:125]
	v_mfma_f32_16x16x32_bf16 v[122:125], v[102:105], v[198:201], v[122:125]
	v_mfma_f32_16x16x32_bf16 v[114:117], v[98:101], v[202:205], v[114:117]
	v_mfma_f32_16x16x32_bf16 v[114:117], v[102:105], v[212:215], v[114:117]
	s_setprio 0
	s_setprio 1
	v_mfma_f32_16x16x32_bf16 v[70:73], v[146:149], v[178:181], v[70:73]
	v_mfma_f32_16x16x32_bf16 v[70:73], v[150:153], v[182:185], v[70:73]
	v_mfma_f32_16x16x32_bf16 v[62:65], v[146:149], v[186:189], v[62:65]
	v_mfma_f32_16x16x32_bf16 v[62:65], v[150:153], v[190:193], v[62:65]
	v_mfma_f32_16x16x32_bf16 v[54:57], v[146:149], v[194:197], v[54:57]
	v_mfma_f32_16x16x32_bf16 v[54:57], v[150:153], v[198:201], v[54:57]
	v_mfma_f32_16x16x32_bf16 v[46:49], v[146:149], v[202:205], v[46:49]
	v_mfma_f32_16x16x32_bf16 v[46:49], v[150:153], v[212:215], v[46:49]
	v_mfma_f32_16x16x32_bf16 v[66:69], v[154:157], v[178:181], v[66:69]
	v_mfma_f32_16x16x32_bf16 v[66:69], v[158:161], v[182:185], v[66:69]
	v_mfma_f32_16x16x32_bf16 v[58:61], v[154:157], v[186:189], v[58:61]
	v_mfma_f32_16x16x32_bf16 v[58:61], v[158:161], v[190:193], v[58:61]
	v_mfma_f32_16x16x32_bf16 v[50:53], v[154:157], v[194:197], v[50:53]
	v_mfma_f32_16x16x32_bf16 v[50:53], v[158:161], v[198:201], v[50:53]
	v_mfma_f32_16x16x32_bf16 v[42:45], v[154:157], v[202:205], v[42:45]
	v_mfma_f32_16x16x32_bf16 v[42:45], v[158:161], v[212:215], v[42:45]
	s_setprio 0
	s_barrier
	s_sleep 1
	s_mov_b64 s[4:5], s[10:11]
	s_add_i32 s56, s56, s17
	ds_read_b128 v[178:181], v210 offset:16384
	ds_read_b128 v[182:185], v210 offset:17408
	ds_read_b128 v[186:189], v210 offset:18432
	ds_read_b128 v[190:193], v210 offset:19456
	ds_read_b128 v[194:197], v210 offset:20480
	ds_read_b128 v[198:201], v210 offset:21504
	ds_read_b128 v[202:205], v210 offset:22528
	ds_read_b128 v[212:215], v210 offset:23552
	s_mov_b32 m0, s56
	s_nop 0
	global_load_lds_dwordx4 v162, s[4:5]
	s_add_i32 m0, s56, 0x2000
	s_nop 0
	global_load_lds_dwordx4 v206, s[4:5]
	s_add_u32 s4, s10, 0x80000
	s_addc_u32 s5, s11, 0
	s_add_i32 s56, s57, s17
	s_mov_b32 m0, s56
	s_nop 0
	global_load_lds_dwordx4 v162, s[4:5]
	s_add_i32 m0, s56, 0x2000
	s_nop 0
	global_load_lds_dwordx4 v206, s[4:5]
	s_mov_b64 s[4:5], s[12:13]
	s_mov_b32 m0, s18
	s_nop 0
	global_load_lds_dwordx4 v1, s[4:5]
	s_mov_b32 m0, s19
	s_nop 0
	global_load_lds_dwordx4 v164, s[4:5]
	s_waitcnt vmcnt(8)
	s_waitcnt lgkmcnt(0)
	s_barrier
; #define PG8_STAGE(bufoff, gbase, voff) do { const char* gb_ = (const char*)(gbase); asm volatile("" : "+s"(gb_)); _Pragma("unroll") for (int _i = 0; _i < 2; ++_i) { unsigned vo_ = (voff)[_i]; asm volatile("" : "+v"(vo_));        \
;         __builtin_amdgcn_global_load_lds((const unsigned*)(gb_ + vo_), (PG8_LAS unsigned*)(lds + (bufoff) + ldsw + _i * 8192), 16, 0, 0); } } while (0)
; #define PG8_LDA(dst, b, h) do { _Pragma("unroll") for (int m = 0; m < 4; ++m) _Pragma("unroll") for (int k = 0; k < 2; ++k) dst[m][k] = *(const PG8_LAS bf16x8*)(lds + PG8_SA(b, h) + aoff + m * 2048 + k * 1024); } while (0)
; #define PG8_LDB(dst, b, h) do { _Pragma("unroll") for (int n = 0; n < 2; ++n) _Pragma("unroll") for (int k = 0; k < 2; ++k) dst[n][k] = *(const PG8_LAS bf16x8*)(lds + PG8_SB(b, h) + boff + n * 2048 + k * 1024); } while (0)
; #define PG8_MMA(ai, bj, At, Bt) do { __builtin_amdgcn_s_setprio(1); _Pragma("unroll") for (int m = 0; m < 4; ++m) _Pragma("unroll") for (int n = 0; n < 2; ++n) _Pragma("unroll") for (int k = 0; k < 2; ++k) \
;         acc[ai][bj][m][n] = __builtin_amdgcn_mfma_f32_16x16x32_bf16(Bt[n][k], At[m][k], acc[ai][bj][m][n], 0, 0, 0); __builtin_amdgcn_s_setprio(0); } while (0)
; #define PG8_WAIT_V(n) asm volatile("s_waitcnt vmcnt(" #n ")" ::: "memory")
; #define PG8_WAIT_L(n) asm volatile("s_waitcnt lgkmcnt(" #n ")" ::: "memory")
; #define PG8_BAR __builtin_amdgcn_s_barrier()
; #define PG8_SCHED __builtin_amdgcn_sched_barrier(0)
; template <class Epi, class Sched, bool ALIGN_EPI = false, bool SP2 = false>
; __device__ __forceinline__ void gemm_phase(PG8_LAS unsigned char* lds, const Gemm g, const Sched& S, const Epi& E) {
;     ...
;             PG8_WAIT_V(8); PG8_WAIT_L(0); PG8_BAR; PG8_MMA(0, 0, At, B0); PG8_MMA(0, 1, At, B1); PG8_BAR; PG8_SCHED;
;             PG8_LDA(At, 0, 1); PG8_STAGE(PG8_SB(0, 0), b2, voffB); PG8_STAGE(PG8_SB(0, 1), b2 + hstep, voffB); PG8_STAGE(PG8_SA(0, 0), a2, voffA);
;             PG8_WAIT_V(8); PG8_WAIT_L(0); PG8_BAR; PG8_MMA(1, 0, At, B0); PG8_MMA(1, 1, At, B1); PG8_BAR; PG8_SCHED;
;             PG8_LDB(B0, 1, 0); PG8_LDB(B1, 1, 1); PG8_SCHED; PG8_LDA(At, 1, 0); PG8_STAGE(PG8_SA(0, 1), a2 + hstep, voffA);
;             PG8_WAIT_V(8); PG8_WAIT_L(0); PG8_BAR; PG8_MMA(0, 0, At, B0); PG8_MMA(0, 1, At, B1); PG8_BAR; PG8_SCHED;
	s_setprio 1
	s_waitcnt lgkmcnt(0)
	v_mfma_f32_16x16x32_bf16 v[110:113], v[26:29], v[178:181], v[110:113]
	v_mfma_f32_16x16x32_bf16 v[110:113], v[30:33], v[182:185], v[110:113]
	v_mfma_f32_16x16x32_bf16 v[94:97], v[26:29], v[186:189], v[94:97]
	v_mfma_f32_16x16x32_bf16 v[94:97], v[30:33], v[190:193], v[94:97]
	v_mfma_f32_16x16x32_bf16 v[86:89], v[26:29], v[194:197], v[86:89]
	v_mfma_f32_16x16x32_bf16 v[86:89], v[30:33], v[198:201], v[86:89]
	v_mfma_f32_16x16x32_bf16 v[26:29], v[26:29], v[202:205], v[78:81]
	v_mfma_f32_16x16x32_bf16 v[26:29], v[30:33], v[212:215], v[26:29]
	v_mfma_f32_16x16x32_bf16 v[106:109], v[98:101], v[178:181], v[106:109]
	v_mfma_f32_16x16x32_bf16 v[106:109], v[102:105], v[182:185], v[106:109]
	v_mfma_f32_16x16x32_bf16 v[90:93], v[98:101], v[186:189], v[90:93]
	v_mfma_f32_16x16x32_bf16 v[90:93], v[102:105], v[190:193], v[90:93]
	v_mfma_f32_16x16x32_bf16 v[82:85], v[98:101], v[194:197], v[82:85]
	v_mfma_f32_16x16x32_bf16 v[82:85], v[102:105], v[198:201], v[82:85]
	v_mfma_f32_16x16x32_bf16 v[30:33], v[98:101], v[202:205], v[74:77]
	v_mfma_f32_16x16x32_bf16 v[30:33], v[102:105], v[212:215], v[30:33]
	s_setprio 0
	s_setprio 1
	v_mfma_f32_16x16x32_bf16 v[38:41], v[146:149], v[178:181], v[38:41]
	v_mfma_f32_16x16x32_bf16 v[38:41], v[150:153], v[182:185], v[38:41]
	v_mfma_f32_16x16x32_bf16 v[22:25], v[146:149], v[186:189], v[22:25]
	v_mfma_f32_16x16x32_bf16 v[22:25], v[150:153], v[190:193], v[22:25]
	v_mfma_f32_16x16x32_bf16 v[14:17], v[146:149], v[194:197], v[14:17]
	v_mfma_f32_16x16x32_bf16 v[14:17], v[150:153], v[198:201], v[14:17]
	v_mfma_f32_16x16x32_bf16 v[6:9], v[146:149], v[202:205], v[6:9]
	v_mfma_f32_16x16x32_bf16 v[6:9], v[150:153], v[212:215], v[6:9]
	v_mfma_f32_16x16x32_bf16 v[34:37], v[154:157], v[178:181], v[34:37]
	v_mfma_f32_16x16x32_bf16 v[34:37], v[158:161], v[182:185], v[34:37]
	v_mfma_f32_16x16x32_bf16 v[18:21], v[154:157], v[186:189], v[18:21]
	v_mfma_f32_16x16x32_bf16 v[18:21], v[158:161], v[190:193], v[18:21]
	v_mfma_f32_16x16x32_bf16 v[10:13], v[154:157], v[194:197], v[10:13]
	v_mfma_f32_16x16x32_bf16 v[10:13], v[158:161], v[198:201], v[10:13]
	v_mfma_f32_16x16x32_bf16 v[2:5], v[154:157], v[202:205], v[2:5]
	v_mfma_f32_16x16x32_bf16 v[2:5], v[158:161], v[212:215], v[2:5]
	s_setprio 0
	s_barrier
	s_sleep 1
	s_add_i32 s56, 0, 0x18000
	s_add_i32 s57, 0, 0x1c000
	ds_read_b128 v[74:77], v244 offset:32768
	ds_read_b128 v[78:81], v244 offset:33792
	ds_read_b128 v[98:101], v244 offset:34816
	ds_read_b128 v[102:105], v244 offset:35840
	ds_read_b128 v[146:149], v244 offset:49152
	ds_read_b128 v[150:153], v244 offset:50176
	ds_read_b128 v[154:157], v244 offset:51200
	ds_read_b128 v[158:161], v244 offset:52224
	s_add_u32 s4, s12, 0x80000
	s_addc_u32 s5, s13, 0
	s_mov_b32 m0, s20
	ds_read_b128 v[178:181], v210 offset:32768
	ds_read_b128 v[182:185], v210 offset:33792
	ds_read_b128 v[186:189], v210 offset:34816
	ds_read_b128 v[190:193], v210 offset:35840
	ds_read_b128 v[194:197], v210 offset:36864
	ds_read_b128 v[198:201], v210 offset:37888
	ds_read_b128 v[202:205], v210 offset:38912
	ds_read_b128 v[212:215], v210 offset:39936
	s_nop 0
	global_load_lds_dwordx4 v1, s[4:5]
	s_mov_b32 m0, s21
	s_nop 0
	global_load_lds_dwordx4 v164, s[4:5]
	s_waitcnt vmcnt(8)
	s_waitcnt lgkmcnt(0)
	s_barrier
	s_setprio 1
	s_waitcnt lgkmcnt(0)
	v_mfma_f32_16x16x32_bf16 v[142:145], v[74:77], v[178:181], v[142:145]
	v_mfma_f32_16x16x32_bf16 v[142:145], v[78:81], v[182:185], v[142:145]
	v_mfma_f32_16x16x32_bf16 v[134:137], v[74:77], v[186:189], v[134:137]
	v_mfma_f32_16x16x32_bf16 v[134:137], v[78:81], v[190:193], v[134:137]
	v_mfma_f32_16x16x32_bf16 v[126:129], v[74:77], v[194:197], v[126:129]
	v_mfma_f32_16x16x32_bf16 v[126:129], v[78:81], v[198:201], v[126:129]
	v_mfma_f32_16x16x32_bf16 v[118:121], v[74:77], v[202:205], v[118:121]
	v_mfma_f32_16x16x32_bf16 v[118:121], v[78:81], v[212:215], v[118:121]
	v_mfma_f32_16x16x32_bf16 v[138:141], v[98:101], v[178:181], v[138:141]
	v_mfma_f32_16x16x32_bf16 v[138:141], v[102:105], v[182:185], v[138:141]
	v_mfma_f32_16x16x32_bf16 v[130:133], v[98:101], v[186:189], v[130:133]
	v_mfma_f32_16x16x32_bf16 v[130:133], v[102:105], v[190:193], v[130:133]
	v_mfma_f32_16x16x32_bf16 v[122:125], v[98:101], v[194:197], v[122:125]
	v_mfma_f32_16x16x32_bf16 v[122:125], v[102:105], v[198:201], v[122:125]
	v_mfma_f32_16x16x32_bf16 v[114:117], v[98:101], v[202:205], v[114:117]
	v_mfma_f32_16x16x32_bf16 v[114:117], v[102:105], v[212:215], v[114:117]
	s_setprio 0
	s_setprio 1
	v_mfma_f32_16x16x32_bf16 v[70:73], v[146:149], v[178:181], v[70:73]
	v_mfma_f32_16x16x32_bf16 v[70:73], v[150:153], v[182:185], v[70:73]
	v_mfma_f32_16x16x32_bf16 v[62:65], v[146:149], v[186:189], v[62:65]
	v_mfma_f32_16x16x32_bf16 v[62:65], v[150:153], v[190:193], v[62:65]
	v_mfma_f32_16x16x32_bf16 v[54:57], v[146:149], v[194:197], v[54:57]
	v_mfma_f32_16x16x32_bf16 v[54:57], v[150:153], v[198:201], v[54:57]
	v_mfma_f32_16x16x32_bf16 v[46:49], v[146:149], v[202:205], v[46:49]
	v_mfma_f32_16x16x32_bf16 v[46:49], v[150:153], v[212:215], v[46:49]
	v_mfma_f32_16x16x32_bf16 v[66:69], v[154:157], v[178:181], v[66:69]
	v_mfma_f32_16x16x32_bf16 v[66:69], v[158:161], v[182:185], v[66:69]
	v_mfma_f32_16x16x32_bf16 v[58:61], v[154:157], v[186:189], v[58:61]
	v_mfma_f32_16x16x32_bf16 v[58:61], v[158:161], v[190:193], v[58:61]
	v_mfma_f32_16x16x32_bf16 v[50:53], v[154:157], v[194:197], v[50:53]
	v_mfma_f32_16x16x32_bf16 v[50:53], v[158:161], v[198:201], v[50:53]
	v_mfma_f32_16x16x32_bf16 v[42:45], v[154:157], v[202:205], v[42:45]
	v_mfma_f32_16x16x32_bf16 v[42:45], v[158:161], v[212:215], v[42:45]
	s_setprio 0
	s_barrier
;     __device__ __forceinline__ void operator()(const f32x4 (&acc)[2][2][4][2], const Unit& u, int wr, int wc, int fr, int fq) const {
;         const int row0 = u.pm * BM + wr * 64 + fr, col0 = u.pn * BM + wc * 32 + 8 * fq, b = (u.pm * BM) / rows_per_batch;
;         const float* g = gate + (size_t)b * gate_bstride + col0;
;         float ssq[2][4];
; #pragma unroll
;         for (int ai = 0; ai < 2; ++ai)
; #pragma unroll
;             for (int m = 0; m < 4; ++m) ssq[ai][m] = 0.f;
;         f32x4 gv[2][2], Gv[2][2];
; #pragma unroll
;         for (int bj = 0; bj < 2; ++bj) { gv[bj][0] = *(const f32x4*)(g + bj * HALF); gv[bj][1] = *(const f32x4*)(g + bj * HALF + 4); Gv[bj][0] = (f32x4){0.f, 0.f, 0.f, 0.f}; Gv[bj][1] = (f32x4){0.f, 0.f, 0.f, 0.f};
;             if (Hn) { const float* sc = scnext + (size_t)b * gate_bstride + col0 + bj * HALF;
;                 Gv[bj][0] = *(const f32x4*)(gnext + col0 + bj * HALF) * (1.0f + *(const f32x4*)(sc)); Gv[bj][1] = *(const f32x4*)(gnext + col0 + bj * HALF + 4) * (1.0f + *(const f32x4*)(sc + 4)); } }
; #pragma unroll
;         for (int bj = 0; bj < 2; ++bj) {
;             const f32x4 g0 = gv[bj][0], g1 = gv[bj][1], G0 = Gv[bj][0], G1 = Gv[bj][1];
; #pragma unroll
;             for (int ai = 0; ai < 2; ++ai)
; #pragma unroll
;                 for (int m = 0; m < 4; ++m) { const size_t off = (size_t)(row0 + ai * HALF + m * 16) * 2048 + col0 + bj * HALF;
;                     f32x4 x0 = __builtin_nontemporal_load((const f32x4*)(base + off)), x1 = __builtin_nontemporal_load((const f32x4*)(base + off + 4));
;                     if constexpr (HAS_DIN) { const u32x4 dw = __builtin_nontemporal_load((const u32x4*)(dbuf + off));
;                         x0 += (f32x4){__builtin_bit_cast(float, dw.x << 16), __builtin_bit_cast(float, dw.x & 0xffff0000u), __builtin_bit_cast(float, dw.y << 16), __builtin_bit_cast(float, dw.y & 0xffff0000u)};
; template <class Epi, class Sched, bool ALIGN_EPI = false, bool SP2 = false>
; __device__ __forceinline__ void gemm_phase(PG8_LAS unsigned char* lds, const Gemm g, const Sched& S, const Epi& E) {
;     ...
;             PG8_LDA(At, 1, 1); PG8_STAGE(PG8_SB(1, 0), b3, voffB); PG8_STAGE(PG8_SB(1, 1), b3 + hstep, voffB); PG8_STAGE(PG8_SA(1, 0), a3, voffA);
;             PG8_WAIT_V(8); PG8_WAIT_L(0); PG8_BAR; PG8_MMA(1, 0, At, B0); PG8_MMA(1, 1, At, B1); PG8_BAR; PG8_SCHED;
	s_sleep 1
	s_add_u32 s4, s10, 0x80
	s_addc_u32 s5, s11, 0
	s_add_i32 s12, s56, s17
	ds_read_b128 v[178:181], v210 offset:49152
	ds_read_b128 v[182:185], v210 offset:50176
	ds_read_b128 v[186:189], v210 offset:51200
	ds_read_b128 v[190:193], v210 offset:52224
	ds_read_b128 v[194:197], v210 offset:53248
	ds_read_b128 v[198:201], v210 offset:54272
	ds_read_b128 v[202:205], v210 offset:55296
	ds_read_b128 v[212:215], v210 offset:56320
	s_mov_b32 m0, s12
	s_nop 0
	global_load_lds_dwordx4 v162, s[4:5]
	s_add_i32 m0, s12, 0x2000
	s_nop 0
	global_load_lds_dwordx4 v206, s[4:5]
	s_add_u32 s4, s10, 0x80080
	s_addc_u32 s5, s11, 0
	s_add_i32 s10, s57, s17
	s_mov_b32 m0, s10
	s_nop 0
	global_load_lds_dwordx4 v162, s[4:5]
	s_add_i32 m0, s10, 0x2000
	s_nop 0
	global_load_lds_dwordx4 v206, s[4:5]
	s_mov_b32 m0, s26
	s_nop 0
	global_load_lds_dwordx4 v1, s[8:9]
	s_mov_b32 m0, s27
	s_nop 0
	global_load_lds_dwordx4 v164, s[8:9]
	s_waitcnt vmcnt(8)
	s_waitcnt lgkmcnt(0)
	s_barrier
	s_setprio 1
	s_waitcnt lgkmcnt(0)
	v_mfma_f32_16x16x32_bf16 v[110:113], v[74:77], v[178:181], v[110:113]
	v_mfma_f32_16x16x32_bf16 v[110:113], v[78:81], v[182:185], v[110:113]
	v_mfma_f32_16x16x32_bf16 v[94:97], v[74:77], v[186:189], v[94:97]
	v_mfma_f32_16x16x32_bf16 v[94:97], v[78:81], v[190:193], v[94:97]
	v_mfma_f32_16x16x32_bf16 v[86:89], v[74:77], v[194:197], v[86:89]
	v_mfma_f32_16x16x32_bf16 v[86:89], v[78:81], v[198:201], v[86:89]
	v_mfma_f32_16x16x32_bf16 v[26:29], v[74:77], v[202:205], v[26:29]
	v_mfma_f32_16x16x32_bf16 v[78:81], v[78:81], v[212:215], v[26:29]
	v_mfma_f32_16x16x32_bf16 v[106:109], v[98:101], v[178:181], v[106:109]
	v_mfma_f32_16x16x32_bf16 v[106:109], v[102:105], v[182:185], v[106:109]
	v_mfma_f32_16x16x32_bf16 v[90:93], v[98:101], v[186:189], v[90:93]
	v_mfma_f32_16x16x32_bf16 v[90:93], v[102:105], v[190:193], v[90:93]
	v_mfma_f32_16x16x32_bf16 v[82:85], v[98:101], v[194:197], v[82:85]
	v_mfma_f32_16x16x32_bf16 v[82:85], v[102:105], v[198:201], v[82:85]
	v_mfma_f32_16x16x32_bf16 v[26:29], v[98:101], v[202:205], v[30:33]
	v_mfma_f32_16x16x32_bf16 v[74:77], v[102:105], v[212:215], v[26:29]
	s_setprio 0
	s_setprio 1
	v_mfma_f32_16x16x32_bf16 v[26:29], v[146:149], v[178:181], v[38:41]
	v_mfma_f32_16x16x32_bf16 v[38:41], v[150:153], v[182:185], v[26:29]
	v_mfma_f32_16x16x32_bf16 v[22:25], v[146:149], v[186:189], v[22:25]
	v_mfma_f32_16x16x32_bf16 v[22:25], v[150:153], v[190:193], v[22:25]
	v_mfma_f32_16x16x32_bf16 v[14:17], v[146:149], v[194:197], v[14:17]
	v_mfma_f32_16x16x32_bf16 v[14:17], v[150:153], v[198:201], v[14:17]
	v_mfma_f32_16x16x32_bf16 v[6:9], v[146:149], v[202:205], v[6:9]
	v_mfma_f32_16x16x32_bf16 v[6:9], v[150:153], v[212:215], v[6:9]
	v_mfma_f32_16x16x32_bf16 v[26:29], v[154:157], v[178:181], v[34:37]
	v_mfma_f32_16x16x32_bf16 v[34:37], v[158:161], v[182:185], v[26:29]
	v_mfma_f32_16x16x32_bf16 v[18:21], v[154:157], v[186:189], v[18:21]
	v_mfma_f32_16x16x32_bf16 v[18:21], v[158:161], v[190:193], v[18:21]
	v_mfma_f32_16x16x32_bf16 v[10:13], v[154:157], v[194:197], v[10:13]
	v_mfma_f32_16x16x32_bf16 v[10:13], v[158:161], v[198:201], v[10:13]
	v_mfma_f32_16x16x32_bf16 v[2:5], v[154:157], v[202:205], v[2:5]
	v_mfma_f32_16x16x32_bf16 v[2:5], v[158:161], v[212:215], v[2:5]
	s_setprio 0
	s_barrier
	s_sleep 1
	s_add_i32 s51, s51, 2
	s_add_u32 s40, s40, 0x100
	s_addc_u32 s49, s49, 0
	s_cmp_gt_u32 s51, 29
	s_mov_b64 s[4:5], s[6:7]
	s_cbranch_scc0 .LBB0_555
	s_ashr_i32 s4, s29, 31
	s_lshr_b32 s4, s4, 27
	s_add_i32 s4, s29, s4
	s_ashr_i32 s4, s4, 5
	v_lshl_or_b32 v148, s33, 8, v209
	s_mul_i32 s7, s4, 0xc000
	v_ashrrev_i32_e32 v149, 31, v148
	s_mul_hi_i32 s6, s4, 0xc000
	s_add_u32 s4, s22, s7
	s_addc_u32 s5, s23, s6
	v_lshlrev_b64 v[26:27], 2, v[148:149]
	v_lshl_add_u64 v[146:147], s[4:5], 0, v[26:27]
	s_add_u32 s4, s24, s7
	s_addc_u32 s5, s25, s6
	v_lshl_add_u64 v[160:161], s[4:5], 0, v[26:27]
	v_lshl_add_u64 v[178:179], s[46:47], 0, v[26:27]
	global_load_dwordx4 v[98:101], v[146:147], off offset:16
	global_load_dwordx4 v[102:105], v[146:147], off
	global_load_dwordx4 v[26:29], v[178:179], off offset:16
	global_load_dwordx4 v[30:33], v[178:179], off
	global_load_dwordx4 v[150:153], v[160:161], off offset:16
	global_load_dwordx4 v[154:157], v[160:161], off
	s_mov_b64 s[4:5], 0x40000
	s_waitcnt vmcnt(0)
	v_pk_mul_f32 v[188:189], v[140:141], v[100:101]
	v_pk_mul_f32 v[142:143], v[142:143], v[102:103]
	v_pk_mul_f32 v[144:145], v[144:145], v[104:105]
	v_pk_mul_f32 v[140:141], v[138:139], v[98:99]
	v_pk_mul_f32 v[136:137], v[136:137], v[104:105]
	v_pk_add_f32 v[156:157], v[156:157], 1.0 op_sel_hi:[1,0]
	v_pk_add_f32 v[154:155], v[154:155], 1.0 op_sel_hi:[1,0]
	v_pk_mul_f32 v[198:199], v[32:33], v[156:157]
	v_pk_mul_f32 v[200:201], v[30:31], v[154:155]
	v_pk_add_f32 v[30:31], v[152:153], 1.0 op_sel_hi:[1,0]
	v_pk_add_f32 v[32:33], v[150:151], 1.0 op_sel_hi:[1,0]
	v_pk_mul_f32 v[202:203], v[28:29], v[30:31]
	v_pk_mul_f32 v[204:205], v[26:27], v[32:33]
	global_load_dwordx4 v[26:29], v[146:147], off offset:528
	global_load_dwordx4 v[30:33], v[146:147], off offset:512
	global_load_dwordx4 v[156:159], v[178:179], off offset:528
	global_load_dwordx4 v[152:155], v[178:179], off offset:512
	s_nop 0
	global_load_dwordx4 v[178:181], v[160:161], off offset:528
	global_load_dwordx4 v[182:185], v[160:161], off offset:512
	v_pk_mul_f32 v[134:135], v[134:135], v[102:103]
	v_pk_mul_f32 v[130:131], v[130:131], v[98:99]
	v_pk_mul_f32 v[132:133], v[132:133], v[100:101]
	v_pk_mul_f32 v[128:129], v[128:129], v[104:105]
	v_pk_mul_f32 v[126:127], v[126:127], v[102:103]
	v_pk_mul_f32 v[122:123], v[122:123], v[98:99]
	v_pk_mul_f32 v[124:125], v[124:125], v[100:101]
	v_pk_mul_f32 v[120:121], v[120:121], v[104:105]
	v_pk_mul_f32 v[118:119], v[118:119], v[102:103]
	v_pk_mul_f32 v[114:115], v[114:115], v[98:99]
	v_pk_mul_f32 v[116:117], v[116:117], v[100:101]
	v_pk_mul_f32 v[112:113], v[112:113], v[104:105]
	v_pk_mul_f32 v[110:111], v[110:111], v[102:103]
	v_pk_mul_f32 v[106:107], v[106:107], v[98:99]
	v_pk_mul_f32 v[108:109], v[108:109], v[100:101]
	v_pk_mul_f32 v[96:97], v[96:97], v[104:105]
	v_pk_mul_f32 v[94:95], v[94:95], v[102:103]
	v_pk_mul_f32 v[90:91], v[90:91], v[98:99]
	v_pk_mul_f32 v[92:93], v[92:93], v[100:101]
	v_pk_mul_f32 v[88:89], v[88:89], v[104:105]
	v_pk_mul_f32 v[86:87], v[86:87], v[102:103]
	v_pk_mul_f32 v[82:83], v[82:83], v[98:99]
	v_pk_mul_f32 v[84:85], v[84:85], v[100:101]
	v_pk_mul_f32 v[80:81], v[80:81], v[104:105]
	v_pk_mul_f32 v[78:79], v[78:79], v[102:103]
	v_pk_mul_f32 v[74:75], v[74:75], v[98:99]
	v_pk_mul_f32 v[76:77], v[76:77], v[100:101]
	s_waitcnt vmcnt(5)
; __device__ __forceinline__ unsigned cvt_pk_bf16(float lo, float hi) { unsigned r; asm volatile("v_cvt_pk_bf16_f32 %0, %1, %2" : "=v"(r) : "v"(lo), "v"(hi)); return r; }
;     __device__ __forceinline__ void operator()(const f32x4 (&acc)[2][2][4][2], const Unit& u, int wr, int wc, int fr, int fq) const {
;     ...
;                 for (int m = 0; m < 4; ++m) { const size_t off = (size_t)(row0 + ai * HALF + m * 16) * 2048 + col0 + bj * HALF;
;                     f32x4 x0 = __builtin_nontemporal_load((const f32x4*)(base + off)), x1 = __builtin_nontemporal_load((const f32x4*)(base + off + 4));
;                     if constexpr (HAS_DIN) { const u32x4 dw = __builtin_nontemporal_load((const u32x4*)(dbuf + off));
;                         x0 += (f32x4){__builtin_bit_cast(float, dw.x << 16), __builtin_bit_cast(float, dw.x & 0xffff0000u), __builtin_bit_cast(float, dw.y << 16), __builtin_bit_cast(float, dw.y & 0xffff0000u)};
;                         x1 += (f32x4){__builtin_bit_cast(float, dw.z << 16), __builtin_bit_cast(float, dw.z & 0xffff0000u), __builtin_bit_cast(float, dw.w << 16), __builtin_bit_cast(float, dw.w & 0xffff0000u)}; }
;                     f32x4 o0, o1;
;                     if constexpr (OUT_DELTA) { const f32x4 d0 = g0 * acc[ai][bj][m][0], d1 = g1 * acc[ai][bj][m][1];
;                         u32x4 w; w.x = cvt_pk_bf16(d0[0], d0[1]); w.y = cvt_pk_bf16(d0[2], d0[3]); w.z = cvt_pk_bf16(d1[0], d1[1]); w.w = cvt_pk_bf16(d1[2], d1[3]);
;                         *(u32x4*)(dbuf + off) = w;
;                         o0 = x0 + (f32x4){__builtin_bit_cast(float, w.x << 16), __builtin_bit_cast(float, w.x & 0xffff0000u), __builtin_bit_cast(float, w.y << 16), __builtin_bit_cast(float, w.y & 0xffff0000u)};
;                         o1 = x1 + (f32x4){__builtin_bit_cast(float, w.z << 16), __builtin_bit_cast(float, w.z & 0xffff0000u), __builtin_bit_cast(float, w.w << 16), __builtin_bit_cast(float, w.w & 0xffff0000u)}; }
;                     else { o0 = x0 + g0 * acc[ai][bj][m][0]; o1 = x1 + g1 * acc[ai][bj][m][1]; *(f32x4*)(out + off) = o0; *(f32x4*)(out + off + 4) = o1; }
;                     if (Hn) { const f32x4 h0 = o0 * G0, h1 = o1 * G1;
;                         u32x4 w; w.x = cvt_pk_bf16(h0[0], h0[1]); w.y = cvt_pk_bf16(h0[2], h0[3]); w.z = cvt_pk_bf16(h1[0], h1[1]); w.w = cvt_pk_bf16(h1[2], h1[3]);
;                         *(u32x4*)(Hn + off) = w;
	v_pk_mul_f32 v[58:59], v[58:59], v[26:27]
	s_waitcnt vmcnt(4)
	v_pk_mul_f32 v[72:73], v[72:73], v[32:33]
	v_pk_mul_f32 v[70:71], v[70:71], v[30:31]
	v_pk_mul_f32 v[64:65], v[64:65], v[32:33]
	v_pk_mul_f32 v[62:63], v[62:63], v[30:31]
	s_waitcnt vmcnt(0)
	v_pk_add_f32 v[146:147], v[184:185], 1.0 op_sel_hi:[1,0]
	v_pk_add_f32 v[160:161], v[182:183], 1.0 op_sel_hi:[1,0]
	v_pk_mul_f32 v[150:151], v[154:155], v[146:147]
	v_pk_add_f32 v[146:147], v[180:181], 1.0 op_sel_hi:[1,0]
	v_pk_mul_f32 v[152:153], v[152:153], v[160:161]
	v_pk_mul_f32 v[154:155], v[158:159], v[146:147]
	v_lshl_add_u32 v146, s29, 8, v207
	v_ashrrev_i32_e32 v147, 31, v146
	v_lshlrev_b64 v[184:185], 11, v[146:147]
	v_lshl_add_u64 v[186:187], v[184:185], 0, v[148:149]
	v_pk_add_f32 v[160:161], v[178:179], 1.0 op_sel_hi:[1,0]
	v_lshl_add_u64 v[178:179], v[186:187], 2, s[44:45]
	v_pk_mul_f32 v[156:157], v[156:157], v[160:161]
	global_load_dwordx4 v[158:161], v[178:179], off nt
	global_load_dwordx4 v[180:183], v[178:179], off offset:16 nt
	v_cvt_pk_bf16_f32 v138, v142, v143
	v_lshlrev_b64 v[142:143], 1, v[186:187]
	v_cvt_pk_bf16_f32 v139, v144, v145
	v_cvt_pk_bf16_f32 v140, v140, v141
	v_cvt_pk_bf16_f32 v141, v188, v189
	v_lshl_add_u64 v[144:145], s[90:91], 0, v[142:143]
	global_store_dwordx4 v[144:145], v[138:141], off
	v_lshlrev_b32_e32 v144, 16, v140
	v_and_b32_e32 v145, 0xffff0000, v140
	v_lshlrev_b32_e32 v140, 16, v141
	v_and_b32_e32 v141, 0xffff0000, v141
	v_lshl_add_u64 v[142:143], s[96:97], 0, v[142:143]
	v_pk_mul_f32 v[60:61], v[60:61], v[28:29]
	v_pk_mul_f32 v[56:57], v[56:57], v[32:33]
	v_pk_mul_f32 v[54:55], v[54:55], v[30:31]
	v_pk_mul_f32 v[50:51], v[50:51], v[26:27]
	v_pk_mul_f32 v[52:53], v[52:53], v[28:29]
	v_pk_mul_f32 v[48:49], v[48:49], v[32:33]
	v_pk_mul_f32 v[46:47], v[46:47], v[30:31]
	v_pk_mul_f32 v[42:43], v[42:43], v[26:27]
	v_pk_mul_f32 v[44:45], v[44:45], v[28:29]
	v_pk_mul_f32 v[40:41], v[40:41], v[32:33]
	v_pk_mul_f32 v[38:39], v[38:39], v[30:31]
	v_pk_mul_f32 v[34:35], v[34:35], v[26:27]
	v_pk_mul_f32 v[36:37], v[36:37], v[28:29]
	v_pk_mul_f32 v[24:25], v[24:25], v[32:33]
	v_pk_mul_f32 v[22:23], v[22:23], v[30:31]
	v_pk_mul_f32 v[18:19], v[18:19], v[26:27]
	v_pk_mul_f32 v[20:21], v[20:21], v[28:29]
	v_pk_mul_f32 v[16:17], v[16:17], v[32:33]
	v_pk_mul_f32 v[14:15], v[14:15], v[30:31]
	v_pk_mul_f32 v[10:11], v[10:11], v[26:27]
	v_pk_mul_f32 v[12:13], v[12:13], v[28:29]
	v_pk_mul_f32 v[8:9], v[8:9], v[32:33]
	v_pk_mul_f32 v[6:7], v[6:7], v[30:31]
	v_pk_mul_f32 v[2:3], v[2:3], v[26:27]
	v_pk_mul_f32 v[4:5], v[4:5], v[28:29]
	s_waitcnt vmcnt(1)
	v_pk_add_f32 v[182:183], v[182:183], v[140:141]
	v_lshlrev_b32_e32 v140, 16, v138
	v_and_b32_e32 v141, 0xffff0000, v138
	v_lshlrev_b32_e32 v138, 16, v139
	v_and_b32_e32 v139, 0xffff0000, v139
	v_pk_add_f32 v[158:159], v[158:159], v[140:141]
	v_pk_add_f32 v[160:161], v[160:161], v[138:139]
	v_pk_mul_f32 v[138:139], v[200:201], v[158:159]
	v_pk_add_f32 v[144:145], v[180:181], v[144:145]
	v_pk_mul_f32 v[140:141], v[198:199], v[160:161]
	v_cvt_pk_bf16_f32 v138, v138, v139
	v_pk_mul_f32 v[180:181], v[202:203], v[182:183]
	v_cvt_pk_bf16_f32 v139, v140, v141
	v_pk_mul_f32 v[186:187], v[204:205], v[144:145]
	s_nop 0
	v_cvt_pk_bf16_f32 v140, v186, v187
	v_cvt_pk_bf16_f32 v141, v180, v181
	global_store_dwordx4 v[142:143], v[138:141], off
	s_nop 1
	v_mul_f32_e32 v138, v159, v159
	v_mul_f32_e32 v139, v161, v161
	v_fmac_f32_e32 v138, v158, v158
	v_fmac_f32_e32 v139, v160, v160
	v_add_f32_e32 v138, v138, v139
	v_mul_f32_e32 v139, v145, v145
	v_mul_f32_e32 v140, v183, v183
	v_fmac_f32_e32 v139, v144, v144
	v_fmac_f32_e32 v140, v182, v182
	v_add_f32_e32 v139, v139, v140
	v_add_f32_e32 v211, v138, v139
	v_or_b32_e32 v138, 16, v146
	v_ashrrev_i32_e32 v139, 31, v138
	v_lshlrev_b64 v[140:141], 11, v[138:139]
	v_lshl_add_u64 v[180:181], v[140:141], 0, v[148:149]
	v_lshl_add_u64 v[138:139], v[180:181], 2, s[44:45]
	global_load_dwordx4 v[142:145], v[138:139], off nt
	global_load_dwordx4 v[158:161], v[138:139], off offset:16 nt
	v_lshlrev_b64 v[180:181], 1, v[180:181]
	v_cvt_pk_bf16_f32 v134, v134, v135
	v_cvt_pk_bf16_f32 v135, v136, v137
	v_cvt_pk_bf16_f32 v136, v130, v131
	v_cvt_pk_bf16_f32 v137, v132, v133
	v_lshl_add_u64 v[130:131], s[90:91], 0, v[180:181]
	global_store_dwordx4 v[130:131], v[134:137], off
	v_lshlrev_b32_e32 v132, 16, v136
	v_and_b32_e32 v133, 0xffff0000, v136
	v_lshlrev_b32_e32 v130, 16, v137
	v_and_b32_e32 v131, 0xffff0000, v137
	v_lshlrev_b32_e32 v136, 16, v134
	v_and_b32_e32 v137, 0xffff0000, v134
	v_lshlrev_b32_e32 v134, 16, v135
	v_and_b32_e32 v135, 0xffff0000, v135
	s_waitcnt vmcnt(2)
	v_pk_add_f32 v[134:135], v[144:145], v[134:135]
	s_waitcnt vmcnt(1)
	v_pk_add_f32 v[130:131], v[160:161], v[130:131]
	v_pk_add_f32 v[136:137], v[142:143], v[136:137]
	v_pk_add_f32 v[132:133], v[158:159], v[132:133]
	v_pk_mul_f32 v[144:145], v[198:199], v[134:135]
	v_pk_mul_f32 v[142:143], v[200:201], v[136:137]
	v_pk_mul_f32 v[158:159], v[202:203], v[130:131]
	v_pk_mul_f32 v[160:161], v[204:205], v[132:133]
	v_cvt_pk_bf16_f32 v142, v142, v143
	v_cvt_pk_bf16_f32 v143, v144, v145
	s_nop 0
	v_cvt_pk_bf16_f32 v144, v160, v161
	v_cvt_pk_bf16_f32 v145, v158, v159
	v_lshl_add_u64 v[158:159], s[96:97], 0, v[180:181]
	global_store_dwordx4 v[158:159], v[142:145], off
	s_nop 1
	v_or_b32_e32 v142, 32, v146
	v_ashrrev_i32_e32 v143, 31, v142
	v_lshlrev_b64 v[144:145], 11, v[142:143]
	v_lshl_add_u64 v[186:187], v[144:145], 0, v[148:149]
	v_lshl_add_u64 v[142:143], v[186:187], 2, s[44:45]
	global_load_dwordx4 v[158:161], v[142:143], off nt
	global_load_dwordx4 v[180:183], v[142:143], off offset:16 nt
	v_lshlrev_b64 v[186:187], 1, v[186:187]
	v_cvt_pk_bf16_f32 v126, v126, v127
	v_cvt_pk_bf16_f32 v127, v128, v129
	v_cvt_pk_bf16_f32 v128, v122, v123
	v_cvt_pk_bf16_f32 v129, v124, v125
	v_lshl_add_u64 v[122:123], s[90:91], 0, v[186:187]
	global_store_dwordx4 v[122:123], v[126:129], off
	v_lshlrev_b32_e32 v124, 16, v128
	v_and_b32_e32 v125, 0xffff0000, v128
	v_lshlrev_b32_e32 v122, 16, v129
	v_and_b32_e32 v123, 0xffff0000, v129
	v_lshlrev_b32_e32 v128, 16, v126
	v_and_b32_e32 v129, 0xffff0000, v126
	v_lshlrev_b32_e32 v126, 16, v127
	v_and_b32_e32 v127, 0xffff0000, v127
	s_waitcnt vmcnt(2)
; __device__ __forceinline__ unsigned cvt_pk_bf16(float lo, float hi) { unsigned r; asm volatile("v_cvt_pk_bf16_f32 %0, %1, %2" : "=v"(r) : "v"(lo), "v"(hi)); return r; }
;     __device__ __forceinline__ void operator()(const f32x4 (&acc)[2][2][4][2], const Unit& u, int wr, int wc, int fr, int fq) const {
;     ...
;                 for (int m = 0; m < 4; ++m) { const size_t off = (size_t)(row0 + ai * HALF + m * 16) * 2048 + col0 + bj * HALF;
;                     f32x4 x0 = __builtin_nontemporal_load((const f32x4*)(base + off)), x1 = __builtin_nontemporal_load((const f32x4*)(base + off + 4));
;                     if constexpr (HAS_DIN) { const u32x4 dw = __builtin_nontemporal_load((const u32x4*)(dbuf + off));
;                         x0 += (f32x4){__builtin_bit_cast(float, dw.x << 16), __builtin_bit_cast(float, dw.x & 0xffff0000u), __builtin_bit_cast(float, dw.y << 16), __builtin_bit_cast(float, dw.y & 0xffff0000u)};
;                         x1 += (f32x4){__builtin_bit_cast(float, dw.z << 16), __builtin_bit_cast(float, dw.z & 0xffff0000u), __builtin_bit_cast(float, dw.w << 16), __builtin_bit_cast(float, dw.w & 0xffff0000u)}; }
;                     f32x4 o0, o1;
;                     if constexpr (OUT_DELTA) { const f32x4 d0 = g0 * acc[ai][bj][m][0], d1 = g1 * acc[ai][bj][m][1];
;                         u32x4 w; w.x = cvt_pk_bf16(d0[0], d0[1]); w.y = cvt_pk_bf16(d0[2], d0[3]); w.z = cvt_pk_bf16(d1[0], d1[1]); w.w = cvt_pk_bf16(d1[2], d1[3]);
;                         *(u32x4*)(dbuf + off) = w;
;                         o0 = x0 + (f32x4){__builtin_bit_cast(float, w.x << 16), __builtin_bit_cast(float, w.x & 0xffff0000u), __builtin_bit_cast(float, w.y << 16), __builtin_bit_cast(float, w.y & 0xffff0000u)};
;                         o1 = x1 + (f32x4){__builtin_bit_cast(float, w.z << 16), __builtin_bit_cast(float, w.z & 0xffff0000u), __builtin_bit_cast(float, w.w << 16), __builtin_bit_cast(float, w.w & 0xffff0000u)}; }
;                     else { o0 = x0 + g0 * acc[ai][bj][m][0]; o1 = x1 + g1 * acc[ai][bj][m][1]; *(f32x4*)(out + off) = o0; *(f32x4*)(out + off + 4) = o1; }
;                     if (Hn) { const f32x4 h0 = o0 * G0, h1 = o1 * G1;
;                         u32x4 w; w.x = cvt_pk_bf16(h0[0], h0[1]); w.y = cvt_pk_bf16(h0[2], h0[3]); w.z = cvt_pk_bf16(h1[0], h1[1]); w.w = cvt_pk_bf16(h1[2], h1[3]);
;                         *(u32x4*)(Hn + off) = w;
	v_pk_add_f32 v[126:127], v[160:161], v[126:127]
	s_waitcnt vmcnt(1)
	v_pk_add_f32 v[122:123], v[182:183], v[122:123]
	v_pk_add_f32 v[128:129], v[158:159], v[128:129]
	v_pk_add_f32 v[124:125], v[180:181], v[124:125]
	v_pk_mul_f32 v[160:161], v[198:199], v[126:127]
	v_pk_mul_f32 v[158:159], v[200:201], v[128:129]
	v_pk_mul_f32 v[180:181], v[202:203], v[122:123]
	v_pk_mul_f32 v[182:183], v[204:205], v[124:125]
	v_cvt_pk_bf16_f32 v158, v158, v159
	v_cvt_pk_bf16_f32 v159, v160, v161
	s_nop 0
	v_cvt_pk_bf16_f32 v160, v182, v183
	v_cvt_pk_bf16_f32 v161, v180, v181
	v_lshl_add_u64 v[180:181], s[96:97], 0, v[186:187]
	global_store_dwordx4 v[180:181], v[158:161], off
	s_nop 1
	v_or_b32_e32 v158, 48, v146
	v_ashrrev_i32_e32 v159, 31, v158
	v_lshlrev_b64 v[160:161], 11, v[158:159]
	v_lshl_add_u64 v[190:191], v[160:161], 0, v[148:149]
	v_lshl_add_u64 v[158:159], v[190:191], 2, s[44:45]
	global_load_dwordx4 v[180:183], v[158:159], off nt
	global_load_dwordx4 v[186:189], v[158:159], off offset:16 nt
	v_lshlrev_b64 v[190:191], 1, v[190:191]
	v_cvt_pk_bf16_f32 v118, v118, v119
	v_cvt_pk_bf16_f32 v119, v120, v121
	v_cvt_pk_bf16_f32 v120, v114, v115
	v_cvt_pk_bf16_f32 v121, v116, v117
	v_lshl_add_u64 v[114:115], s[90:91], 0, v[190:191]
	global_store_dwordx4 v[114:115], v[118:121], off
	v_lshlrev_b32_e32 v116, 16, v120
	v_and_b32_e32 v117, 0xffff0000, v120
	v_lshlrev_b32_e32 v114, 16, v121
	v_and_b32_e32 v115, 0xffff0000, v121
	v_lshlrev_b32_e32 v120, 16, v118
	v_and_b32_e32 v121, 0xffff0000, v118
	v_lshlrev_b32_e32 v118, 16, v119
	v_and_b32_e32 v119, 0xffff0000, v119
	s_waitcnt vmcnt(2)
	v_pk_add_f32 v[118:119], v[182:183], v[118:119]
	s_waitcnt vmcnt(1)
	v_pk_add_f32 v[114:115], v[188:189], v[114:115]
	v_pk_add_f32 v[120:121], v[180:181], v[120:121]
	v_pk_add_f32 v[116:117], v[186:187], v[116:117]
	v_pk_mul_f32 v[182:183], v[198:199], v[118:119]
	v_pk_mul_f32 v[180:181], v[200:201], v[120:121]
	v_pk_mul_f32 v[186:187], v[202:203], v[114:115]
	v_pk_mul_f32 v[188:189], v[204:205], v[116:117]
	v_cvt_pk_bf16_f32 v180, v180, v181
	v_cvt_pk_bf16_f32 v181, v182, v183
	s_nop 0
	v_cvt_pk_bf16_f32 v182, v188, v189
	v_cvt_pk_bf16_f32 v183, v186, v187
	v_lshl_add_u64 v[186:187], s[96:97], 0, v[190:191]
	global_store_dwordx4 v[186:187], v[180:183], off
	s_nop 1
	v_lshl_add_u64 v[182:183], v[184:185], 0, s[4:5]
	v_lshl_add_u64 v[194:195], v[182:183], 0, v[148:149]
	v_lshl_add_u64 v[180:181], v[194:195], 2, s[44:45]
	global_load_dwordx4 v[186:189], v[180:181], off nt
	global_load_dwordx4 v[190:193], v[180:181], off offset:16 nt
	v_lshlrev_b64 v[194:195], 1, v[194:195]
	v_cvt_pk_bf16_f32 v110, v110, v111
	v_cvt_pk_bf16_f32 v111, v112, v113
	v_cvt_pk_bf16_f32 v112, v106, v107
	v_cvt_pk_bf16_f32 v113, v108, v109
	v_lshl_add_u64 v[106:107], s[90:91], 0, v[194:195]
	global_store_dwordx4 v[106:107], v[110:113], off
	v_lshlrev_b32_e32 v108, 16, v112
	v_and_b32_e32 v109, 0xffff0000, v112
	v_lshlrev_b32_e32 v106, 16, v113
	v_and_b32_e32 v107, 0xffff0000, v113
	v_lshlrev_b32_e32 v112, 16, v110
	v_and_b32_e32 v113, 0xffff0000, v110
	v_lshlrev_b32_e32 v110, 16, v111
	v_and_b32_e32 v111, 0xffff0000, v111
	s_mov_b64 s[4:5], 0x48000
	s_waitcnt vmcnt(2)
	v_pk_add_f32 v[110:111], v[188:189], v[110:111]
	s_waitcnt vmcnt(1)
	v_pk_add_f32 v[106:107], v[192:193], v[106:107]
	v_pk_add_f32 v[112:113], v[186:187], v[112:113]
	v_pk_add_f32 v[108:109], v[190:191], v[108:109]
	v_pk_mul_f32 v[188:189], v[198:199], v[110:111]
	v_pk_mul_f32 v[186:187], v[200:201], v[112:113]
	v_pk_mul_f32 v[190:191], v[202:203], v[106:107]
	v_pk_mul_f32 v[192:193], v[204:205], v[108:109]
	v_cvt_pk_bf16_f32 v186, v186, v187
	v_cvt_pk_bf16_f32 v187, v188, v189
	s_nop 0
	v_cvt_pk_bf16_f32 v188, v192, v193
	v_cvt_pk_bf16_f32 v189, v190, v191
	v_lshl_add_u64 v[190:191], s[96:97], 0, v[194:195]
	global_store_dwordx4 v[190:191], v[186:189], off
	s_nop 1
	v_lshl_add_u64 v[188:189], v[184:185], 0, s[4:5]
	v_lshl_add_u64 v[212:213], v[188:189], 0, v[148:149]
	v_lshl_add_u64 v[186:187], v[212:213], 2, s[44:45]
	global_load_dwordx4 v[190:193], v[186:187], off nt
	global_load_dwordx4 v[194:197], v[186:187], off offset:16 nt
	v_lshlrev_b64 v[212:213], 1, v[212:213]
	v_cvt_pk_bf16_f32 v94, v94, v95
	v_cvt_pk_bf16_f32 v95, v96, v97
	v_cvt_pk_bf16_f32 v96, v90, v91
	v_cvt_pk_bf16_f32 v97, v92, v93
	v_lshl_add_u64 v[90:91], s[90:91], 0, v[212:213]
	global_store_dwordx4 v[90:91], v[94:97], off
	v_lshlrev_b32_e32 v92, 16, v96
	v_and_b32_e32 v93, 0xffff0000, v96
	v_lshlrev_b32_e32 v90, 16, v97
	v_and_b32_e32 v91, 0xffff0000, v97
	v_lshlrev_b32_e32 v96, 16, v94
	v_and_b32_e32 v97, 0xffff0000, v94
	v_lshlrev_b32_e32 v94, 16, v95
	v_and_b32_e32 v95, 0xffff0000, v95
	s_mov_b64 s[4:5], 0x50000
	s_waitcnt vmcnt(2)
	v_pk_add_f32 v[94:95], v[192:193], v[94:95]
	s_waitcnt vmcnt(1)
	v_pk_add_f32 v[90:91], v[196:197], v[90:91]
	v_pk_add_f32 v[96:97], v[190:191], v[96:97]
	v_pk_add_f32 v[92:93], v[194:195], v[92:93]
	v_pk_mul_f32 v[192:193], v[198:199], v[94:95]
	v_pk_mul_f32 v[190:191], v[200:201], v[96:97]
	v_pk_mul_f32 v[194:195], v[202:203], v[90:91]
	v_pk_mul_f32 v[196:197], v[204:205], v[92:93]
	v_cvt_pk_bf16_f32 v190, v190, v191
	v_cvt_pk_bf16_f32 v191, v192, v193
	s_nop 0
	v_cvt_pk_bf16_f32 v192, v196, v197
	v_cvt_pk_bf16_f32 v193, v194, v195
	v_lshl_add_u64 v[194:195], s[96:97], 0, v[212:213]
	global_store_dwordx4 v[194:195], v[190:193], off
	s_nop 1
	v_lshl_add_u64 v[192:193], v[184:185], 0, s[4:5]
	v_lshl_add_u64 v[220:221], v[192:193], 0, v[148:149]
	v_lshl_add_u64 v[190:191], v[220:221], 2, s[44:45]
	global_load_dwordx4 v[194:197], v[190:191], off nt
	global_load_dwordx4 v[212:215], v[190:191], off offset:16 nt
	v_lshlrev_b64 v[220:221], 1, v[220:221]
	v_cvt_pk_bf16_f32 v86, v86, v87
	v_cvt_pk_bf16_f32 v87, v88, v89
	v_cvt_pk_bf16_f32 v88, v82, v83
	v_cvt_pk_bf16_f32 v89, v84, v85
	v_lshl_add_u64 v[82:83], s[90:91], 0, v[220:221]
	global_store_dwordx4 v[82:83], v[86:89], off
	v_lshlrev_b32_e32 v84, 16, v88
	v_and_b32_e32 v85, 0xffff0000, v88
	v_lshlrev_b32_e32 v82, 16, v89
	v_and_b32_e32 v83, 0xffff0000, v89
	v_lshlrev_b32_e32 v88, 16, v86
	v_and_b32_e32 v89, 0xffff0000, v86
	v_lshlrev_b32_e32 v86, 16, v87
	v_and_b32_e32 v87, 0xffff0000, v87
	s_mov_b64 s[4:5], 0x58000
	s_waitcnt vmcnt(2)
; __device__ __forceinline__ unsigned cvt_pk_bf16(float lo, float hi) { unsigned r; asm volatile("v_cvt_pk_bf16_f32 %0, %1, %2" : "=v"(r) : "v"(lo), "v"(hi)); return r; }
;     __device__ __forceinline__ void operator()(const f32x4 (&acc)[2][2][4][2], const Unit& u, int wr, int wc, int fr, int fq) const {
;     ...
;                 for (int m = 0; m < 4; ++m) { const size_t off = (size_t)(row0 + ai * HALF + m * 16) * 2048 + col0 + bj * HALF;
;                     f32x4 x0 = __builtin_nontemporal_load((const f32x4*)(base + off)), x1 = __builtin_nontemporal_load((const f32x4*)(base + off + 4));
;                     if constexpr (HAS_DIN) { const u32x4 dw = __builtin_nontemporal_load((const u32x4*)(dbuf + off));
;                         x0 += (f32x4){__builtin_bit_cast(float, dw.x << 16), __builtin_bit_cast(float, dw.x & 0xffff0000u), __builtin_bit_cast(float, dw.y << 16), __builtin_bit_cast(float, dw.y & 0xffff0000u)};
;                         x1 += (f32x4){__builtin_bit_cast(float, dw.z << 16), __builtin_bit_cast(float, dw.z & 0xffff0000u), __builtin_bit_cast(float, dw.w << 16), __builtin_bit_cast(float, dw.w & 0xffff0000u)}; }
;                     f32x4 o0, o1;
;                     if constexpr (OUT_DELTA) { const f32x4 d0 = g0 * acc[ai][bj][m][0], d1 = g1 * acc[ai][bj][m][1];
;                         u32x4 w; w.x = cvt_pk_bf16(d0[0], d0[1]); w.y = cvt_pk_bf16(d0[2], d0[3]); w.z = cvt_pk_bf16(d1[0], d1[1]); w.w = cvt_pk_bf16(d1[2], d1[3]);
;                         *(u32x4*)(dbuf + off) = w;
;                         o0 = x0 + (f32x4){__builtin_bit_cast(float, w.x << 16), __builtin_bit_cast(float, w.x & 0xffff0000u), __builtin_bit_cast(float, w.y << 16), __builtin_bit_cast(float, w.y & 0xffff0000u)};
;                         o1 = x1 + (f32x4){__builtin_bit_cast(float, w.z << 16), __builtin_bit_cast(float, w.z & 0xffff0000u), __builtin_bit_cast(float, w.w << 16), __builtin_bit_cast(float, w.w & 0xffff0000u)}; }
;                     else { o0 = x0 + g0 * acc[ai][bj][m][0]; o1 = x1 + g1 * acc[ai][bj][m][1]; *(f32x4*)(out + off) = o0; *(f32x4*)(out + off + 4) = o1; }
;                     if (Hn) { const f32x4 h0 = o0 * G0, h1 = o1 * G1;
;                         u32x4 w; w.x = cvt_pk_bf16(h0[0], h0[1]); w.y = cvt_pk_bf16(h0[2], h0[3]); w.z = cvt_pk_bf16(h1[0], h1[1]); w.w = cvt_pk_bf16(h1[2], h1[3]);
;                         *(u32x4*)(Hn + off) = w;
	v_pk_add_f32 v[86:87], v[196:197], v[86:87]
	s_waitcnt vmcnt(1)
	v_pk_add_f32 v[82:83], v[214:215], v[82:83]
	v_pk_add_f32 v[88:89], v[194:195], v[88:89]
	v_pk_add_f32 v[84:85], v[212:213], v[84:85]
	v_pk_mul_f32 v[196:197], v[198:199], v[86:87]
	v_pk_mul_f32 v[194:195], v[200:201], v[88:89]
	v_pk_mul_f32 v[212:213], v[202:203], v[82:83]
	v_pk_mul_f32 v[214:215], v[204:205], v[84:85]
	v_cvt_pk_bf16_f32 v194, v194, v195
	v_cvt_pk_bf16_f32 v195, v196, v197
	s_nop 0
	v_cvt_pk_bf16_f32 v196, v214, v215
	v_cvt_pk_bf16_f32 v197, v212, v213
	v_lshl_add_u64 v[212:213], s[96:97], 0, v[220:221]
	global_store_dwordx4 v[212:213], v[194:197], off
	s_nop 1
	v_lshl_add_u64 v[196:197], v[184:185], 0, s[4:5]
	v_lshl_add_u64 v[224:225], v[196:197], 0, v[148:149]
	v_lshl_add_u64 v[194:195], v[224:225], 2, s[44:45]
	global_load_dwordx4 v[212:215], v[194:195], off nt
	global_load_dwordx4 v[220:223], v[194:195], off offset:16 nt
	v_lshlrev_b64 v[102:103], 1, v[224:225]
	v_cvt_pk_bf16_f32 v78, v78, v79
	v_cvt_pk_bf16_f32 v79, v80, v81
	v_cvt_pk_bf16_f32 v80, v74, v75
	v_cvt_pk_bf16_f32 v81, v76, v77
	v_lshl_add_u64 v[74:75], s[90:91], 0, v[102:103]
	global_store_dwordx4 v[74:75], v[78:81], off
	v_lshlrev_b32_e32 v76, 16, v80
	v_and_b32_e32 v77, 0xffff0000, v80
	v_lshlrev_b32_e32 v74, 16, v81
	v_and_b32_e32 v75, 0xffff0000, v81
	v_lshlrev_b32_e32 v80, 16, v78
	v_and_b32_e32 v81, 0xffff0000, v78
	v_lshlrev_b32_e32 v78, 16, v79
	v_and_b32_e32 v79, 0xffff0000, v79
	v_lshl_add_u64 v[102:103], s[96:97], 0, v[102:103]
	v_or_b32_e32 v148, 0x80, v148
	s_waitcnt vmcnt(2)
	v_pk_add_f32 v[78:79], v[214:215], v[78:79]
	v_pk_add_f32 v[80:81], v[212:213], v[80:81]
	s_waitcnt vmcnt(1)
	v_pk_add_f32 v[74:75], v[222:223], v[74:75]
	v_pk_add_f32 v[76:77], v[220:221], v[76:77]
	v_pk_mul_f32 v[100:101], v[198:199], v[78:79]
	v_pk_mul_f32 v[98:99], v[200:201], v[80:81]
	v_pk_mul_f32 v[104:105], v[202:203], v[74:75]
	v_pk_mul_f32 v[198:199], v[204:205], v[76:77]
	v_cvt_pk_bf16_f32 v98, v98, v99
	v_cvt_pk_bf16_f32 v99, v100, v101
	s_nop 0
	v_cvt_pk_bf16_f32 v100, v198, v199
	v_cvt_pk_bf16_f32 v101, v104, v105
	global_store_dwordx4 v[102:103], v[98:101], off
	global_load_dwordx4 v[100:103], v[178:179], off offset:512 nt
	global_load_dwordx4 v[198:201], v[178:179], off offset:528 nt
	v_lshl_add_u64 v[98:99], v[184:185], 0, v[148:149]
	v_pk_mul_f32 v[104:105], v[68:69], v[28:29]
	v_pk_mul_f32 v[68:69], v[66:67], v[26:27]
	v_cvt_pk_bf16_f32 v66, v70, v71
	v_cvt_pk_bf16_f32 v67, v72, v73
	s_nop 0
	v_cvt_pk_bf16_f32 v68, v68, v69
	v_cvt_pk_bf16_f32 v69, v104, v105
	v_lshlrev_b64 v[104:105], 1, v[98:99]
	v_lshl_add_u64 v[70:71], s[90:91], 0, v[104:105]
	global_store_dwordx4 v[70:71], v[66:69], off
	v_lshlrev_b32_e32 v72, 16, v68
	v_and_b32_e32 v73, 0xffff0000, v68
	v_lshlrev_b32_e32 v68, 16, v69
	v_and_b32_e32 v69, 0xffff0000, v69
	s_waitcnt vmcnt(1)
	v_pk_add_f32 v[70:71], v[200:201], v[68:69]
	v_lshlrev_b32_e32 v68, 16, v66
	v_and_b32_e32 v69, 0xffff0000, v66
	v_lshlrev_b32_e32 v66, 16, v67
	v_and_b32_e32 v67, 0xffff0000, v67
	v_pk_add_f32 v[98:99], v[102:103], v[66:67]
	v_pk_add_f32 v[100:101], v[100:101], v[68:69]
	v_pk_add_f32 v[72:73], v[198:199], v[72:73]
	v_pk_mul_f32 v[68:69], v[150:151], v[98:99]
	v_pk_mul_f32 v[66:67], v[152:153], v[100:101]
	v_pk_mul_f32 v[102:103], v[154:155], v[70:71]
	v_pk_mul_f32 v[178:179], v[156:157], v[72:73]
	v_cvt_pk_bf16_f32 v66, v66, v67
	v_cvt_pk_bf16_f32 v67, v68, v69
	s_nop 0
	v_cvt_pk_bf16_f32 v68, v178, v179
	v_cvt_pk_bf16_f32 v69, v102, v103
	v_lshl_add_u64 v[102:103], s[96:97], 0, v[104:105]
	global_store_dwordx4 v[102:103], v[66:69], off
	s_nop 1
	v_mul_f32_e32 v66, v101, v101
	v_mul_f32_e32 v67, v99, v99
	v_fmac_f32_e32 v66, v100, v100
	v_fmac_f32_e32 v67, v98, v98
	v_add_f32_e32 v66, v66, v67
	v_mul_f32_e32 v67, v73, v73
	v_mul_f32_e32 v68, v71, v71
	v_fmac_f32_e32 v67, v72, v72
	v_fmac_f32_e32 v68, v70, v70
	v_add_f32_e32 v67, v67, v68
	global_load_dwordx4 v[68:71], v[138:139], off offset:512 nt
	global_load_dwordx4 v[98:101], v[138:139], off offset:528 nt
	v_lshl_add_u64 v[72:73], v[140:141], 0, v[148:149]
	v_lshlrev_b64 v[72:73], 1, v[72:73]
	v_cvt_pk_bf16_f32 v62, v62, v63
	v_cvt_pk_bf16_f32 v63, v64, v65
	v_cvt_pk_bf16_f32 v64, v58, v59
	v_cvt_pk_bf16_f32 v65, v60, v61
	v_lshl_add_u64 v[58:59], s[90:91], 0, v[72:73]
	global_store_dwordx4 v[58:59], v[62:65], off
	v_lshlrev_b32_e32 v60, 16, v64
	v_and_b32_e32 v61, 0xffff0000, v64
	v_lshlrev_b32_e32 v58, 16, v65
	v_and_b32_e32 v59, 0xffff0000, v65
	v_lshlrev_b32_e32 v64, 16, v62
	v_and_b32_e32 v65, 0xffff0000, v62
	v_lshlrev_b32_e32 v62, 16, v63
	v_and_b32_e32 v63, 0xffff0000, v63
	v_lshl_add_u64 v[72:73], s[96:97], 0, v[72:73]
	v_add_f32_e32 v66, v66, v67
	v_add_f32_e32 v66, v211, v66
	s_waitcnt vmcnt(2)
	v_pk_add_f32 v[62:63], v[70:71], v[62:63]
	v_pk_add_f32 v[64:65], v[68:69], v[64:65]
	s_waitcnt vmcnt(1)
	v_pk_add_f32 v[58:59], v[100:101], v[58:59]
	v_pk_add_f32 v[60:61], v[98:99], v[60:61]
	v_pk_mul_f32 v[70:71], v[150:151], v[62:63]
	v_pk_mul_f32 v[68:69], v[152:153], v[64:65]
	v_pk_mul_f32 v[98:99], v[154:155], v[58:59]
	v_pk_mul_f32 v[100:101], v[156:157], v[60:61]
	v_cvt_pk_bf16_f32 v68, v68, v69
	v_cvt_pk_bf16_f32 v69, v70, v71
	s_nop 0
	v_cvt_pk_bf16_f32 v70, v100, v101
	v_cvt_pk_bf16_f32 v71, v98, v99
	global_store_dwordx4 v[72:73], v[68:71], off
	global_load_dwordx4 v[68:71], v[142:143], off offset:512 nt
	s_nop 0
	global_load_dwordx4 v[98:101], v[142:143], off offset:528 nt
	v_lshl_add_u64 v[72:73], v[144:145], 0, v[148:149]
	v_lshlrev_b64 v[72:73], 1, v[72:73]
	v_cvt_pk_bf16_f32 v54, v54, v55
	v_cvt_pk_bf16_f32 v55, v56, v57
	v_cvt_pk_bf16_f32 v56, v50, v51
	v_cvt_pk_bf16_f32 v57, v52, v53
	v_lshl_add_u64 v[50:51], s[90:91], 0, v[72:73]
	global_store_dwordx4 v[50:51], v[54:57], off
	v_lshlrev_b32_e32 v52, 16, v56
	v_and_b32_e32 v53, 0xffff0000, v56
	v_lshlrev_b32_e32 v50, 16, v57
	v_and_b32_e32 v51, 0xffff0000, v57
	v_lshlrev_b32_e32 v56, 16, v54
	v_and_b32_e32 v57, 0xffff0000, v54
	v_lshlrev_b32_e32 v54, 16, v55
	v_and_b32_e32 v55, 0xffff0000, v55
	v_lshl_add_u64 v[72:73], s[96:97], 0, v[72:73]
	s_waitcnt vmcnt(2)
; __device__ __forceinline__ unsigned cvt_pk_bf16(float lo, float hi) { unsigned r; asm volatile("v_cvt_pk_bf16_f32 %0, %1, %2" : "=v"(r) : "v"(lo), "v"(hi)); return r; }
;     __device__ __forceinline__ void operator()(const f32x4 (&acc)[2][2][4][2], const Unit& u, int wr, int wc, int fr, int fq) const {
;     ...
;                 for (int m = 0; m < 4; ++m) { const size_t off = (size_t)(row0 + ai * HALF + m * 16) * 2048 + col0 + bj * HALF;
;                     f32x4 x0 = __builtin_nontemporal_load((const f32x4*)(base + off)), x1 = __builtin_nontemporal_load((const f32x4*)(base + off + 4));
;                     if constexpr (HAS_DIN) { const u32x4 dw = __builtin_nontemporal_load((const u32x4*)(dbuf + off));
;                         x0 += (f32x4){__builtin_bit_cast(float, dw.x << 16), __builtin_bit_cast(float, dw.x & 0xffff0000u), __builtin_bit_cast(float, dw.y << 16), __builtin_bit_cast(float, dw.y & 0xffff0000u)};
;                         x1 += (f32x4){__builtin_bit_cast(float, dw.z << 16), __builtin_bit_cast(float, dw.z & 0xffff0000u), __builtin_bit_cast(float, dw.w << 16), __builtin_bit_cast(float, dw.w & 0xffff0000u)}; }
;                     f32x4 o0, o1;
;                     if constexpr (OUT_DELTA) { const f32x4 d0 = g0 * acc[ai][bj][m][0], d1 = g1 * acc[ai][bj][m][1];
;                         u32x4 w; w.x = cvt_pk_bf16(d0[0], d0[1]); w.y = cvt_pk_bf16(d0[2], d0[3]); w.z = cvt_pk_bf16(d1[0], d1[1]); w.w = cvt_pk_bf16(d1[2], d1[3]);
;                         *(u32x4*)(dbuf + off) = w;
;                         o0 = x0 + (f32x4){__builtin_bit_cast(float, w.x << 16), __builtin_bit_cast(float, w.x & 0xffff0000u), __builtin_bit_cast(float, w.y << 16), __builtin_bit_cast(float, w.y & 0xffff0000u)};
;                         o1 = x1 + (f32x4){__builtin_bit_cast(float, w.z << 16), __builtin_bit_cast(float, w.z & 0xffff0000u), __builtin_bit_cast(float, w.w << 16), __builtin_bit_cast(float, w.w & 0xffff0000u)}; }
;                     else { o0 = x0 + g0 * acc[ai][bj][m][0]; o1 = x1 + g1 * acc[ai][bj][m][1]; *(f32x4*)(out + off) = o0; *(f32x4*)(out + off + 4) = o1; }
;                     if (Hn) { const f32x4 h0 = o0 * G0, h1 = o1 * G1;
;                         u32x4 w; w.x = cvt_pk_bf16(h0[0], h0[1]); w.y = cvt_pk_bf16(h0[2], h0[3]); w.z = cvt_pk_bf16(h1[0], h1[1]); w.w = cvt_pk_bf16(h1[2], h1[3]);
;                         *(u32x4*)(Hn + off) = w;
	v_pk_add_f32 v[54:55], v[70:71], v[54:55]
	v_pk_add_f32 v[56:57], v[68:69], v[56:57]
	s_waitcnt vmcnt(1)
	v_pk_add_f32 v[50:51], v[100:101], v[50:51]
	v_pk_add_f32 v[52:53], v[98:99], v[52:53]
	v_pk_mul_f32 v[70:71], v[150:151], v[54:55]
	v_pk_mul_f32 v[68:69], v[152:153], v[56:57]
	v_pk_mul_f32 v[98:99], v[154:155], v[50:51]
	v_pk_mul_f32 v[100:101], v[156:157], v[52:53]
	v_cvt_pk_bf16_f32 v68, v68, v69
	v_cvt_pk_bf16_f32 v69, v70, v71
	s_nop 0
	v_cvt_pk_bf16_f32 v70, v100, v101
	v_cvt_pk_bf16_f32 v71, v98, v99
	global_store_dwordx4 v[72:73], v[68:71], off
	global_load_dwordx4 v[68:71], v[158:159], off offset:512 nt
	s_nop 0
	global_load_dwordx4 v[98:101], v[158:159], off offset:528 nt
	v_lshl_add_u64 v[72:73], v[160:161], 0, v[148:149]
	v_lshlrev_b64 v[72:73], 1, v[72:73]
	v_cvt_pk_bf16_f32 v46, v46, v47
	v_cvt_pk_bf16_f32 v47, v48, v49
	v_cvt_pk_bf16_f32 v48, v42, v43
	v_cvt_pk_bf16_f32 v49, v44, v45
	v_lshl_add_u64 v[42:43], s[90:91], 0, v[72:73]
	global_store_dwordx4 v[42:43], v[46:49], off
	v_lshlrev_b32_e32 v44, 16, v48
	v_and_b32_e32 v45, 0xffff0000, v48
	v_lshlrev_b32_e32 v42, 16, v49
	v_and_b32_e32 v43, 0xffff0000, v49
	v_lshlrev_b32_e32 v48, 16, v46
	v_and_b32_e32 v49, 0xffff0000, v46
	v_lshlrev_b32_e32 v46, 16, v47
	v_and_b32_e32 v47, 0xffff0000, v47
	v_lshl_add_u64 v[72:73], s[96:97], 0, v[72:73]
	s_waitcnt vmcnt(2)
	v_pk_add_f32 v[46:47], v[70:71], v[46:47]
	v_pk_add_f32 v[48:49], v[68:69], v[48:49]
	s_waitcnt vmcnt(1)
	v_pk_add_f32 v[42:43], v[100:101], v[42:43]
	v_pk_add_f32 v[44:45], v[98:99], v[44:45]
	v_pk_mul_f32 v[70:71], v[150:151], v[46:47]
	v_pk_mul_f32 v[68:69], v[152:153], v[48:49]
	v_pk_mul_f32 v[98:99], v[154:155], v[42:43]
	v_pk_mul_f32 v[100:101], v[156:157], v[44:45]
	v_cvt_pk_bf16_f32 v68, v68, v69
	v_cvt_pk_bf16_f32 v69, v70, v71
	s_nop 0
	v_cvt_pk_bf16_f32 v70, v100, v101
	v_cvt_pk_bf16_f32 v71, v98, v99
	global_store_dwordx4 v[72:73], v[68:71], off
	global_load_dwordx4 v[68:71], v[180:181], off offset:512 nt
	s_nop 0
	global_load_dwordx4 v[98:101], v[180:181], off offset:528 nt
	v_lshl_add_u64 v[72:73], v[182:183], 0, v[148:149]
	v_lshlrev_b64 v[72:73], 1, v[72:73]
	v_cvt_pk_bf16_f32 v38, v38, v39
	v_cvt_pk_bf16_f32 v39, v40, v41
	v_cvt_pk_bf16_f32 v40, v34, v35
	v_cvt_pk_bf16_f32 v41, v36, v37
	v_lshl_add_u64 v[34:35], s[90:91], 0, v[72:73]
	global_store_dwordx4 v[34:35], v[38:41], off
	v_lshlrev_b32_e32 v36, 16, v40
	v_and_b32_e32 v37, 0xffff0000, v40
	v_lshlrev_b32_e32 v34, 16, v41
	v_and_b32_e32 v35, 0xffff0000, v41
	v_lshlrev_b32_e32 v40, 16, v38
	v_and_b32_e32 v41, 0xffff0000, v38
	v_lshlrev_b32_e32 v38, 16, v39
	v_and_b32_e32 v39, 0xffff0000, v39
	v_lshl_add_u64 v[72:73], s[96:97], 0, v[72:73]
	s_waitcnt vmcnt(2)
	v_pk_add_f32 v[38:39], v[70:71], v[38:39]
	v_pk_add_f32 v[40:41], v[68:69], v[40:41]
	s_waitcnt vmcnt(1)
	v_pk_add_f32 v[34:35], v[100:101], v[34:35]
	v_pk_add_f32 v[36:37], v[98:99], v[36:37]
	v_pk_mul_f32 v[70:71], v[150:151], v[38:39]
	v_pk_mul_f32 v[68:69], v[152:153], v[40:41]
	v_pk_mul_f32 v[98:99], v[154:155], v[34:35]
	v_pk_mul_f32 v[100:101], v[156:157], v[36:37]
	v_cvt_pk_bf16_f32 v68, v68, v69
	v_cvt_pk_bf16_f32 v69, v70, v71
	s_nop 0
	v_cvt_pk_bf16_f32 v70, v100, v101
	v_cvt_pk_bf16_f32 v71, v98, v99
	global_store_dwordx4 v[72:73], v[68:71], off
	global_load_dwordx4 v[68:71], v[186:187], off offset:512 nt
	s_nop 0
	global_load_dwordx4 v[98:101], v[186:187], off offset:528 nt
	v_lshl_add_u64 v[72:73], v[188:189], 0, v[148:149]
	v_lshlrev_b64 v[72:73], 1, v[72:73]
	v_cvt_pk_bf16_f32 v22, v22, v23
	v_cvt_pk_bf16_f32 v23, v24, v25
	v_cvt_pk_bf16_f32 v24, v18, v19
	v_cvt_pk_bf16_f32 v25, v20, v21
	v_lshl_add_u64 v[18:19], s[90:91], 0, v[72:73]
	global_store_dwordx4 v[18:19], v[22:25], off
	v_lshlrev_b32_e32 v20, 16, v24
	v_and_b32_e32 v21, 0xffff0000, v24
	v_lshlrev_b32_e32 v18, 16, v25
	v_and_b32_e32 v19, 0xffff0000, v25
	v_lshlrev_b32_e32 v24, 16, v22
	v_and_b32_e32 v25, 0xffff0000, v22
	v_lshlrev_b32_e32 v22, 16, v23
	v_and_b32_e32 v23, 0xffff0000, v23
	v_lshl_add_u64 v[72:73], s[96:97], 0, v[72:73]
	s_waitcnt vmcnt(2)
	v_pk_add_f32 v[22:23], v[70:71], v[22:23]
	v_pk_add_f32 v[24:25], v[68:69], v[24:25]
	s_waitcnt vmcnt(1)
; __device__ __forceinline__ unsigned cvt_pk_bf16(float lo, float hi) { unsigned r; asm volatile("v_cvt_pk_bf16_f32 %0, %1, %2" : "=v"(r) : "v"(lo), "v"(hi)); return r; }
;     __device__ __forceinline__ void operator()(const f32x4 (&acc)[2][2][4][2], const Unit& u, int wr, int wc, int fr, int fq) const {
;     ...
;                 for (int m = 0; m < 4; ++m) { const size_t off = (size_t)(row0 + ai * HALF + m * 16) * 2048 + col0 + bj * HALF;
;                     f32x4 x0 = __builtin_nontemporal_load((const f32x4*)(base + off)), x1 = __builtin_nontemporal_load((const f32x4*)(base + off + 4));
;                     if constexpr (HAS_DIN) { const u32x4 dw = __builtin_nontemporal_load((const u32x4*)(dbuf + off));
;                         x0 += (f32x4){__builtin_bit_cast(float, dw.x << 16), __builtin_bit_cast(float, dw.x & 0xffff0000u), __builtin_bit_cast(float, dw.y << 16), __builtin_bit_cast(float, dw.y & 0xffff0000u)};
;                         x1 += (f32x4){__builtin_bit_cast(float, dw.z << 16), __builtin_bit_cast(float, dw.z & 0xffff0000u), __builtin_bit_cast(float, dw.w << 16), __builtin_bit_cast(float, dw.w & 0xffff0000u)}; }
;                     f32x4 o0, o1;
;                     if constexpr (OUT_DELTA) { const f32x4 d0 = g0 * acc[ai][bj][m][0], d1 = g1 * acc[ai][bj][m][1];
;                         u32x4 w; w.x = cvt_pk_bf16(d0[0], d0[1]); w.y = cvt_pk_bf16(d0[2], d0[3]); w.z = cvt_pk_bf16(d1[0], d1[1]); w.w = cvt_pk_bf16(d1[2], d1[3]);
;                         *(u32x4*)(dbuf + off) = w;
;                         o0 = x0 + (f32x4){__builtin_bit_cast(float, w.x << 16), __builtin_bit_cast(float, w.x & 0xffff0000u), __builtin_bit_cast(float, w.y << 16), __builtin_bit_cast(float, w.y & 0xffff0000u)};
;                         o1 = x1 + (f32x4){__builtin_bit_cast(float, w.z << 16), __builtin_bit_cast(float, w.z & 0xffff0000u), __builtin_bit_cast(float, w.w << 16), __builtin_bit_cast(float, w.w & 0xffff0000u)}; }
;                     else { o0 = x0 + g0 * acc[ai][bj][m][0]; o1 = x1 + g1 * acc[ai][bj][m][1]; *(f32x4*)(out + off) = o0; *(f32x4*)(out + off + 4) = o1; }
;                     if (Hn) { const f32x4 h0 = o0 * G0, h1 = o1 * G1;
;                         u32x4 w; w.x = cvt_pk_bf16(h0[0], h0[1]); w.y = cvt_pk_bf16(h0[2], h0[3]); w.z = cvt_pk_bf16(h1[0], h1[1]); w.w = cvt_pk_bf16(h1[2], h1[3]);
;                         *(u32x4*)(Hn + off) = w;
	v_pk_add_f32 v[18:19], v[100:101], v[18:19]
	v_pk_add_f32 v[20:21], v[98:99], v[20:21]
	v_pk_mul_f32 v[70:71], v[150:151], v[22:23]
	v_pk_mul_f32 v[68:69], v[152:153], v[24:25]
	v_pk_mul_f32 v[98:99], v[154:155], v[18:19]
	v_pk_mul_f32 v[100:101], v[156:157], v[20:21]
	v_cvt_pk_bf16_f32 v68, v68, v69
	v_cvt_pk_bf16_f32 v69, v70, v71
	s_nop 0
	v_cvt_pk_bf16_f32 v70, v100, v101
	v_cvt_pk_bf16_f32 v71, v98, v99
	global_store_dwordx4 v[72:73], v[68:71], off
	global_load_dwordx4 v[68:71], v[190:191], off offset:512 nt
	s_nop 0
	global_load_dwordx4 v[98:101], v[190:191], off offset:528 nt
	v_lshl_add_u64 v[72:73], v[192:193], 0, v[148:149]
	v_lshlrev_b64 v[72:73], 1, v[72:73]
	v_cvt_pk_bf16_f32 v14, v14, v15
	v_cvt_pk_bf16_f32 v15, v16, v17
	v_cvt_pk_bf16_f32 v16, v10, v11
	v_cvt_pk_bf16_f32 v17, v12, v13
	v_lshl_add_u64 v[10:11], s[90:91], 0, v[72:73]
	global_store_dwordx4 v[10:11], v[14:17], off
	v_lshlrev_b32_e32 v12, 16, v16
	v_and_b32_e32 v13, 0xffff0000, v16
	v_lshlrev_b32_e32 v10, 16, v17
	v_and_b32_e32 v11, 0xffff0000, v17
	v_lshlrev_b32_e32 v16, 16, v14
	v_and_b32_e32 v17, 0xffff0000, v14
	v_lshlrev_b32_e32 v14, 16, v15
	v_and_b32_e32 v15, 0xffff0000, v15
	v_lshl_add_u64 v[72:73], s[96:97], 0, v[72:73]
	s_waitcnt vmcnt(2)
	v_pk_add_f32 v[14:15], v[70:71], v[14:15]
	v_pk_add_f32 v[16:17], v[68:69], v[16:17]
	s_waitcnt vmcnt(1)
	v_pk_add_f32 v[10:11], v[100:101], v[10:11]
	v_pk_add_f32 v[12:13], v[98:99], v[12:13]
	v_pk_mul_f32 v[70:71], v[150:151], v[14:15]
	v_pk_mul_f32 v[68:69], v[152:153], v[16:17]
	v_pk_mul_f32 v[98:99], v[154:155], v[10:11]
	v_pk_mul_f32 v[100:101], v[156:157], v[12:13]
	v_cvt_pk_bf16_f32 v68, v68, v69
	v_cvt_pk_bf16_f32 v69, v70, v71
	s_nop 0
	v_cvt_pk_bf16_f32 v70, v100, v101
	v_cvt_pk_bf16_f32 v71, v98, v99
	global_store_dwordx4 v[72:73], v[68:71], off
	global_load_dwordx4 v[68:71], v[194:195], off offset:512 nt
	s_nop 0
	global_load_dwordx4 v[98:101], v[194:195], off offset:528 nt
	v_lshl_add_u64 v[72:73], v[196:197], 0, v[148:149]
	v_lshlrev_b64 v[30:31], 1, v[72:73]
	v_cvt_pk_bf16_f32 v6, v6, v7
	v_cvt_pk_bf16_f32 v7, v8, v9
	v_cvt_pk_bf16_f32 v8, v2, v3
	v_cvt_pk_bf16_f32 v9, v4, v5
	v_lshl_add_u64 v[2:3], s[90:91], 0, v[30:31]
	global_store_dwordx4 v[2:3], v[6:9], off
	v_lshlrev_b32_e32 v4, 16, v8
	v_and_b32_e32 v5, 0xffff0000, v8
	v_lshlrev_b32_e32 v2, 16, v9
	v_and_b32_e32 v3, 0xffff0000, v9
	v_lshlrev_b32_e32 v8, 16, v6
	v_and_b32_e32 v9, 0xffff0000, v6
	v_lshlrev_b32_e32 v6, 16, v7
	v_and_b32_e32 v7, 0xffff0000, v7
	v_lshl_add_u64 v[30:31], s[96:97], 0, v[30:31]
	s_waitcnt vmcnt(2)
	v_pk_add_f32 v[8:9], v[68:69], v[8:9]
	v_pk_add_f32 v[6:7], v[70:71], v[6:7]
	v_pk_mul_f32 v[26:27], v[152:153], v[8:9]
	s_waitcnt vmcnt(1)
	v_pk_add_f32 v[2:3], v[100:101], v[2:3]
	v_pk_add_f32 v[4:5], v[98:99], v[4:5]
	v_pk_mul_f32 v[28:29], v[150:151], v[6:7]
	v_cvt_pk_bf16_f32 v26, v26, v27
	v_pk_mul_f32 v[32:33], v[154:155], v[2:3]
	v_cvt_pk_bf16_f32 v27, v28, v29
	v_pk_mul_f32 v[68:69], v[156:157], v[4:5]
	s_nop 0
	v_cvt_pk_bf16_f32 v28, v68, v69
	v_cvt_pk_bf16_f32 v29, v32, v33
	global_store_dwordx4 v[30:31], v[26:29], off
	s_nop 1
	v_and_b32_e32 v27, 64, v218
	v_xor_b32_e32 v26, 16, v218
	v_add_u32_e32 v27, 64, v27
	v_cmp_lt_i32_e32 vcc, v26, v27
	s_nop 1
	v_cndmask_b32_e32 v26, v218, v26, vcc
	v_lshlrev_b32_e32 v28, 2, v26
	v_xor_b32_e32 v26, 32, v218
	v_cmp_lt_i32_e32 vcc, v26, v27
	s_nop 1
	v_cndmask_b32_e32 v26, v218, v26, vcc
	v_lshlrev_b32_e32 v29, 2, v26
	ds_bpermute_b32 v26, v28, v66
	s_waitcnt lgkmcnt(0)
	v_add_f32_e32 v30, v66, v26
	ds_bpermute_b32 v31, v29, v30
	v_lshl_add_u64 v[26:27], v[146:147], 3, s[42:43]
	s_and_saveexec_b64 s[4:5], s[0:1]
	s_mov_b32 s8, 0x2f800000
	s_mov_b32 s9, 0xcf800000
	s_cbranch_execz .LBB0_558
	s_waitcnt lgkmcnt(0)
	v_add_f32_e32 v30, v30, v31
	v_mul_f32_e32 v30, 0x47800000, v30
	v_rndne_f32_e32 v30, v30
	v_mul_f32_e64 v31, |v30|, s8
	v_floor_f32_e32 v31, v31
	v_fma_f32 v32, v31, s9, |v30|
	v_cvt_u32_f32_e32 v32, v32
	v_cvt_u32_f32_e32 v31, v31
	v_ashrrev_i32_e32 v33, 31, v30
	v_xor_b32_e32 v30, v32, v33
	v_xor_b32_e32 v31, v31, v33
	v_sub_co_u32_e32 v30, vcc, v30, v33
	s_nop 1
	v_subb_co_u32_e32 v31, vcc, v31, v33, vcc
	global_atomic_add_x2 v[26:27], v[30:31], off

; #define PG8_STAGE(bufoff, gbase, voff) do { const char* gb_ = (const char*)(gbase); asm volatile("" : "+s"(gb_)); _Pragma("unroll") for (int _i = 0; _i < 2; ++_i) { unsigned vo_ = (voff)[_i]; asm volatile("" : "+v"(vo_));        \
;         __builtin_amdgcn_global_load_lds((const unsigned*)(gb_ + vo_), (PG8_LAS unsigned*)(lds + (bufoff) + ldsw + _i * 8192), 16, 0, 0); } } while (0)
; #define PG8_LDA(dst, b, h) do { _Pragma("unroll") for (int m = 0; m < 4; ++m) _Pragma("unroll") for (int k = 0; k < 2; ++k) dst[m][k] = *(const PG8_LAS bf16x8*)(lds + PG8_SA(b, h) + aoff + m * 2048 + k * 1024); } while (0)
; #define PG8_WAIT_V(n) asm volatile("s_waitcnt vmcnt(" #n ")" ::: "memory")
; #define PG8_WAIT_L(n) asm volatile("s_waitcnt lgkmcnt(" #n ")" ::: "memory")
; template <class Epi, class Sched, bool ALIGN_EPI = false, bool SP2 = false>
; __device__ __forceinline__ void gemm_phase(PG8_LAS unsigned char* lds, const Gemm g, const Sched& S, const Epi& E) {
;     ...
;             const bool last = (t == nt - 2);
;             const char* a1 = cA + (size_t)(t + 1) * kstep;
;             const char* a2 = last ? nA : cA + (size_t)(t + 2) * kstep; const char* b2 = last ? nB : cB + (size_t)(t + 2) * kstep;
;             const char* a3 = a2 + kstep; const char* b3 = b2 + kstep;
;             if (last && has_next) S.a_ready(nxt);
;             if constexpr (SP2) {
;             PG8_LDB(B0, 0, 0); PG8_LDB(B1, 0, 1); PG8_SCHED; PG8_LDA(At, 0, 0); PG8_STAGE(PG8_SA(1, 1), a1 + hstep, voffA);
;             PG8_WAIT_V(8); PG8_WAIT_L(0); PG8_BAR; PG8_MMA(0, 0, At, B0); PG8_MMA(0, 1, At, B1); PG8_BAR; PG8_SCHED;
;             PG8_LDA(At, 0, 1); PG8_STAGE(PG8_SB(0, 0), b2, voffB); PG8_STAGE(PG8_SB(0, 1), b2 + hstep, voffB); PG8_STAGE(PG8_SA(0, 0), a2, voffA);
;             PG8_WAIT_V(8); PG8_WAIT_L(0); PG8_BAR; PG8_MMA(1, 0, At, B0); PG8_MMA(1, 1, At, B1); PG8_BAR; PG8_SCHED;
;             PG8_LDB(B0, 1, 0); PG8_LDB(B1, 1, 1); PG8_SCHED; PG8_LDA(At, 1, 0); PG8_STAGE(PG8_SA(0, 1), a2 + hstep, voffA);
;             PG8_WAIT_V(8); PG8_WAIT_L(0); PG8_BAR; PG8_MMA(0, 0, At, B0); PG8_MMA(0, 1, At, B1); PG8_BAR; PG8_SCHED;
;             PG8_LDA(At, 1, 1); PG8_STAGE(PG8_SB(1, 0), b3, voffB); PG8_STAGE(PG8_SB(1, 1), b3 + hstep, voffB); PG8_STAGE(PG8_SA(1, 0), a3, voffA);
;             PG8_WAIT_V(8); PG8_WAIT_L(0); PG8_BAR; PG8_MMA(1, 0, At, B0); PG8_MMA(1, 1, At, B1); PG8_BAR; PG8_SCHED;
.LBB0_634:
	s_add_u32 s16, s14, 0x100
	s_addc_u32 s17, s15, 0
	s_cmp_eq_u32 s53, 28
	s_cselect_b32 s22, s49, s16
	s_cselect_b32 s23, s7, s17
	s_cselect_b32 s20, s50, s51
	s_cselect_b32 s21, s5, s52
	s_add_u32 s18, s22, 0x80
	s_addc_u32 s19, s23, 0
	s_add_i32 s54, 0, 0x10000
	s_add_i32 s55, 0, 0x14000
	ds_read_b128 v[82:85], v244
	ds_read_b128 v[86:89], v244 offset:1024
	ds_read_b128 v[90:93], v244 offset:2048
	ds_read_b128 v[94:97], v244 offset:3072
	ds_read_b128 v[146:149], v244 offset:16384
	ds_read_b128 v[150:153], v244 offset:17408
	ds_read_b128 v[154:157], v244 offset:18432
	ds_read_b128 v[158:161], v244 offset:19456
	s_add_u32 s14, s14, 0x80080
	s_addc_u32 s15, s15, 0
	ds_read_b128 v[178:181], v188
	ds_read_b128 v[190:193], v188 offset:1024
	ds_read_b128 v[194:197], v188 offset:2048
	ds_read_b128 v[198:201], v188 offset:3072
	ds_read_b128 v[202:205], v188 offset:4096
	ds_read_b128 v[206:209], v188 offset:5120
	ds_read_b128 v[210:213], v188 offset:6144
	ds_read_b128 v[220:223], v188 offset:7168
	s_add_i32 m0, s27, 0xc000
	s_nop 0
	global_load_lds_dwordx4 v1, s[14:15]
	s_add_i32 m0, s27, 0xe000
	s_nop 0
	global_load_lds_dwordx4 v164, s[14:15]
	s_waitcnt vmcnt(8)
	s_waitcnt lgkmcnt(0)
	s_barrier
	s_setprio 1
	s_waitcnt lgkmcnt(0)
	v_mfma_f32_16x16x32_bf16 v[142:145], v[82:85], v[178:181], v[142:145]
	v_mfma_f32_16x16x32_bf16 v[142:145], v[86:89], v[190:193], v[142:145]
	v_mfma_f32_16x16x32_bf16 v[126:129], v[82:85], v[194:197], v[126:129]
	v_mfma_f32_16x16x32_bf16 v[126:129], v[86:89], v[198:201], v[126:129]
	v_mfma_f32_16x16x32_bf16 v[110:113], v[82:85], v[202:205], v[110:113]
	v_mfma_f32_16x16x32_bf16 v[110:113], v[86:89], v[206:209], v[110:113]
	v_mfma_f32_16x16x32_bf16 v[78:81], v[82:85], v[210:213], v[78:81]
	v_mfma_f32_16x16x32_bf16 v[78:81], v[86:89], v[220:223], v[78:81]
	v_mfma_f32_16x16x32_bf16 v[138:141], v[90:93], v[178:181], v[138:141]
	v_mfma_f32_16x16x32_bf16 v[138:141], v[94:97], v[190:193], v[138:141]
	v_mfma_f32_16x16x32_bf16 v[122:125], v[90:93], v[194:197], v[122:125]
	v_mfma_f32_16x16x32_bf16 v[122:125], v[94:97], v[198:201], v[122:125]
	v_mfma_f32_16x16x32_bf16 v[106:109], v[90:93], v[202:205], v[106:109]
	v_mfma_f32_16x16x32_bf16 v[106:109], v[94:97], v[206:209], v[106:109]
	v_mfma_f32_16x16x32_bf16 v[74:77], v[90:93], v[210:213], v[74:77]
	v_mfma_f32_16x16x32_bf16 v[74:77], v[94:97], v[220:223], v[74:77]
	s_setprio 0
	s_setprio 1
	v_mfma_f32_16x16x32_bf16 v[134:137], v[146:149], v[178:181], v[134:137]
	v_mfma_f32_16x16x32_bf16 v[134:137], v[150:153], v[190:193], v[134:137]
	v_mfma_f32_16x16x32_bf16 v[118:121], v[146:149], v[194:197], v[118:121]
	v_mfma_f32_16x16x32_bf16 v[118:121], v[150:153], v[198:201], v[118:121]
	v_mfma_f32_16x16x32_bf16 v[102:105], v[146:149], v[202:205], v[102:105]
	v_mfma_f32_16x16x32_bf16 v[102:105], v[150:153], v[206:209], v[102:105]
	v_mfma_f32_16x16x32_bf16 v[70:73], v[146:149], v[210:213], v[70:73]
	v_mfma_f32_16x16x32_bf16 v[70:73], v[150:153], v[220:223], v[70:73]
	v_mfma_f32_16x16x32_bf16 v[130:133], v[154:157], v[178:181], v[130:133]
	v_mfma_f32_16x16x32_bf16 v[130:133], v[158:161], v[190:193], v[130:133]
	v_mfma_f32_16x16x32_bf16 v[114:117], v[154:157], v[194:197], v[114:117]
	v_mfma_f32_16x16x32_bf16 v[114:117], v[158:161], v[198:201], v[114:117]
	v_mfma_f32_16x16x32_bf16 v[98:101], v[154:157], v[202:205], v[98:101]
	v_mfma_f32_16x16x32_bf16 v[98:101], v[158:161], v[206:209], v[98:101]
	v_mfma_f32_16x16x32_bf16 v[66:69], v[154:157], v[210:213], v[66:69]
	v_mfma_f32_16x16x32_bf16 v[66:69], v[158:161], v[220:223], v[66:69]
	s_setprio 0
	s_barrier
	s_sleep 1
	s_mov_b64 s[14:15], s[20:21]
	s_add_i32 s54, s54, s26
	ds_read_b128 v[178:181], v188 offset:16384
	ds_read_b128 v[190:193], v188 offset:17408
	ds_read_b128 v[194:197], v188 offset:18432
	ds_read_b128 v[198:201], v188 offset:19456
	ds_read_b128 v[202:205], v188 offset:20480
	ds_read_b128 v[206:209], v188 offset:21504
	ds_read_b128 v[210:213], v188 offset:22528
	ds_read_b128 v[220:223], v188 offset:23552
	s_mov_b32 m0, s54
	s_nop 0
	global_load_lds_dwordx4 v162, s[14:15]
	s_add_i32 m0, s54, 0x2000
	s_nop 0
	global_load_lds_dwordx4 v184, s[14:15]
	s_add_u32 s14, s20, 0x80000
	s_addc_u32 s15, s21, 0
	s_add_i32 s54, s55, s26
	s_mov_b32 m0, s54
	s_nop 0
	global_load_lds_dwordx4 v162, s[14:15]
	s_add_i32 m0, s54, 0x2000
	s_nop 0
	global_load_lds_dwordx4 v184, s[14:15]
	s_mov_b64 s[14:15], s[22:23]
	s_mov_b32 m0, s27
	s_nop 0
	global_load_lds_dwordx4 v1, s[14:15]
	s_mov_b32 m0, s28
	s_nop 0
	global_load_lds_dwordx4 v164, s[14:15]
	s_waitcnt vmcnt(8)
	s_waitcnt lgkmcnt(0)
	s_barrier
; #define PG8_STAGE(bufoff, gbase, voff) do { const char* gb_ = (const char*)(gbase); asm volatile("" : "+s"(gb_)); _Pragma("unroll") for (int _i = 0; _i < 2; ++_i) { unsigned vo_ = (voff)[_i]; asm volatile("" : "+v"(vo_));        \
;         __builtin_amdgcn_global_load_lds((const unsigned*)(gb_ + vo_), (PG8_LAS unsigned*)(lds + (bufoff) + ldsw + _i * 8192), 16, 0, 0); } } while (0)
; #define PG8_LDA(dst, b, h) do { _Pragma("unroll") for (int m = 0; m < 4; ++m) _Pragma("unroll") for (int k = 0; k < 2; ++k) dst[m][k] = *(const PG8_LAS bf16x8*)(lds + PG8_SA(b, h) + aoff + m * 2048 + k * 1024); } while (0)
; #define PG8_LDB(dst, b, h) do { _Pragma("unroll") for (int n = 0; n < 2; ++n) _Pragma("unroll") for (int k = 0; k < 2; ++k) dst[n][k] = *(const PG8_LAS bf16x8*)(lds + PG8_SB(b, h) + boff + n * 2048 + k * 1024); } while (0)
; #define PG8_MMA(ai, bj, At, Bt) do { __builtin_amdgcn_s_setprio(1); _Pragma("unroll") for (int m = 0; m < 4; ++m) _Pragma("unroll") for (int n = 0; n < 2; ++n) _Pragma("unroll") for (int k = 0; k < 2; ++k) \
;         acc[ai][bj][m][n] = __builtin_amdgcn_mfma_f32_16x16x32_bf16(Bt[n][k], At[m][k], acc[ai][bj][m][n], 0, 0, 0); __builtin_amdgcn_s_setprio(0); } while (0)
; #define PG8_WAIT_V(n) asm volatile("s_waitcnt vmcnt(" #n ")" ::: "memory")
; #define PG8_WAIT_L(n) asm volatile("s_waitcnt lgkmcnt(" #n ")" ::: "memory")
; #define PG8_BAR __builtin_amdgcn_s_barrier()
; #define PG8_SCHED __builtin_amdgcn_sched_barrier(0)
; template <class Epi, class Sched, bool ALIGN_EPI = false, bool SP2 = false>
; __device__ __forceinline__ void gemm_phase(PG8_LAS unsigned char* lds, const Gemm g, const Sched& S, const Epi& E) {
;     ...
;             PG8_WAIT_V(8); PG8_WAIT_L(0); PG8_BAR; PG8_MMA(0, 0, At, B0); PG8_MMA(0, 1, At, B1); PG8_BAR; PG8_SCHED;
;             PG8_LDA(At, 0, 1); PG8_STAGE(PG8_SB(0, 0), b2, voffB); PG8_STAGE(PG8_SB(0, 1), b2 + hstep, voffB); PG8_STAGE(PG8_SA(0, 0), a2, voffA);
;             PG8_WAIT_V(8); PG8_WAIT_L(0); PG8_BAR; PG8_MMA(1, 0, At, B0); PG8_MMA(1, 1, At, B1); PG8_BAR; PG8_SCHED;
;             PG8_LDB(B0, 1, 0); PG8_LDB(B1, 1, 1); PG8_SCHED; PG8_LDA(At, 1, 0); PG8_STAGE(PG8_SA(0, 1), a2 + hstep, voffA);
;             PG8_WAIT_V(8); PG8_WAIT_L(0); PG8_BAR; PG8_MMA(0, 0, At, B0); PG8_MMA(0, 1, At, B1); PG8_BAR; PG8_SCHED;
	s_setprio 1
	s_waitcnt lgkmcnt(0)
	v_mfma_f32_16x16x32_bf16 v[62:65], v[82:85], v[178:181], v[62:65]
	v_mfma_f32_16x16x32_bf16 v[62:65], v[86:89], v[190:193], v[62:65]
	v_mfma_f32_16x16x32_bf16 v[46:49], v[82:85], v[194:197], v[46:49]
	v_mfma_f32_16x16x32_bf16 v[46:49], v[86:89], v[198:201], v[46:49]
	v_mfma_f32_16x16x32_bf16 v[30:33], v[82:85], v[202:205], v[30:33]
	v_mfma_f32_16x16x32_bf16 v[30:33], v[86:89], v[206:209], v[30:33]
	v_mfma_f32_16x16x32_bf16 v[14:17], v[82:85], v[210:213], v[14:17]
	v_mfma_f32_16x16x32_bf16 v[14:17], v[86:89], v[220:223], v[14:17]
	v_mfma_f32_16x16x32_bf16 v[58:61], v[90:93], v[178:181], v[58:61]
	v_mfma_f32_16x16x32_bf16 v[58:61], v[94:97], v[190:193], v[58:61]
	v_mfma_f32_16x16x32_bf16 v[42:45], v[90:93], v[194:197], v[42:45]
	v_mfma_f32_16x16x32_bf16 v[42:45], v[94:97], v[198:201], v[42:45]
	v_mfma_f32_16x16x32_bf16 v[26:29], v[90:93], v[202:205], v[26:29]
	v_mfma_f32_16x16x32_bf16 v[26:29], v[94:97], v[206:209], v[26:29]
	v_mfma_f32_16x16x32_bf16 v[10:13], v[90:93], v[210:213], v[10:13]
	v_mfma_f32_16x16x32_bf16 v[10:13], v[94:97], v[220:223], v[10:13]
	s_setprio 0
	s_setprio 1
	v_mfma_f32_16x16x32_bf16 v[54:57], v[146:149], v[178:181], v[54:57]
	v_mfma_f32_16x16x32_bf16 v[54:57], v[150:153], v[190:193], v[54:57]
	v_mfma_f32_16x16x32_bf16 v[38:41], v[146:149], v[194:197], v[38:41]
	v_mfma_f32_16x16x32_bf16 v[38:41], v[150:153], v[198:201], v[38:41]
	v_mfma_f32_16x16x32_bf16 v[22:25], v[146:149], v[202:205], v[22:25]
	v_mfma_f32_16x16x32_bf16 v[22:25], v[150:153], v[206:209], v[22:25]
	v_mfma_f32_16x16x32_bf16 v[6:9], v[146:149], v[210:213], v[6:9]
	v_mfma_f32_16x16x32_bf16 v[6:9], v[150:153], v[220:223], v[6:9]
	v_mfma_f32_16x16x32_bf16 v[50:53], v[154:157], v[178:181], v[50:53]
	v_mfma_f32_16x16x32_bf16 v[50:53], v[158:161], v[190:193], v[50:53]
	v_mfma_f32_16x16x32_bf16 v[34:37], v[154:157], v[194:197], v[34:37]
	v_mfma_f32_16x16x32_bf16 v[34:37], v[158:161], v[198:201], v[34:37]
	v_mfma_f32_16x16x32_bf16 v[18:21], v[154:157], v[202:205], v[18:21]
	v_mfma_f32_16x16x32_bf16 v[18:21], v[158:161], v[206:209], v[18:21]
	v_mfma_f32_16x16x32_bf16 v[2:5], v[154:157], v[210:213], v[2:5]
	v_mfma_f32_16x16x32_bf16 v[2:5], v[158:161], v[220:223], v[2:5]
	s_setprio 0
	s_barrier
	s_sleep 1
	s_add_i32 s54, 0, 0x18000
	s_add_i32 s55, 0, 0x1c000
	ds_read_b128 v[82:85], v244 offset:32768
	ds_read_b128 v[86:89], v244 offset:33792
	ds_read_b128 v[90:93], v244 offset:34816
	ds_read_b128 v[94:97], v244 offset:35840
	ds_read_b128 v[146:149], v244 offset:49152
	ds_read_b128 v[150:153], v244 offset:50176
	ds_read_b128 v[154:157], v244 offset:51200
	ds_read_b128 v[158:161], v244 offset:52224
	s_add_u32 s14, s22, 0x80000
	s_addc_u32 s15, s23, 0
	s_mov_b32 m0, s29
	ds_read_b128 v[178:181], v188 offset:32768
	ds_read_b128 v[190:193], v188 offset:33792
	ds_read_b128 v[194:197], v188 offset:34816
	ds_read_b128 v[198:201], v188 offset:35840
	ds_read_b128 v[202:205], v188 offset:36864
	ds_read_b128 v[206:209], v188 offset:37888
	ds_read_b128 v[210:213], v188 offset:38912
	ds_read_b128 v[220:223], v188 offset:39936
	s_nop 0
	global_load_lds_dwordx4 v1, s[14:15]
	s_mov_b32 m0, s33
	s_nop 0
	global_load_lds_dwordx4 v164, s[14:15]
	s_waitcnt vmcnt(8)
	s_waitcnt lgkmcnt(0)
	s_barrier
	s_setprio 1
	s_waitcnt lgkmcnt(0)
	v_mfma_f32_16x16x32_bf16 v[142:145], v[82:85], v[178:181], v[142:145]
	v_mfma_f32_16x16x32_bf16 v[142:145], v[86:89], v[190:193], v[142:145]
	v_mfma_f32_16x16x32_bf16 v[126:129], v[82:85], v[194:197], v[126:129]
	v_mfma_f32_16x16x32_bf16 v[126:129], v[86:89], v[198:201], v[126:129]
	v_mfma_f32_16x16x32_bf16 v[110:113], v[82:85], v[202:205], v[110:113]
	v_mfma_f32_16x16x32_bf16 v[110:113], v[86:89], v[206:209], v[110:113]
	v_mfma_f32_16x16x32_bf16 v[78:81], v[82:85], v[210:213], v[78:81]
	v_mfma_f32_16x16x32_bf16 v[78:81], v[86:89], v[220:223], v[78:81]
	v_mfma_f32_16x16x32_bf16 v[138:141], v[90:93], v[178:181], v[138:141]
	v_mfma_f32_16x16x32_bf16 v[138:141], v[94:97], v[190:193], v[138:141]
	v_mfma_f32_16x16x32_bf16 v[122:125], v[90:93], v[194:197], v[122:125]
	v_mfma_f32_16x16x32_bf16 v[122:125], v[94:97], v[198:201], v[122:125]
	v_mfma_f32_16x16x32_bf16 v[106:109], v[90:93], v[202:205], v[106:109]
	v_mfma_f32_16x16x32_bf16 v[106:109], v[94:97], v[206:209], v[106:109]
	v_mfma_f32_16x16x32_bf16 v[74:77], v[90:93], v[210:213], v[74:77]
	v_mfma_f32_16x16x32_bf16 v[74:77], v[94:97], v[220:223], v[74:77]
	s_setprio 0
	s_setprio 1
	v_mfma_f32_16x16x32_bf16 v[134:137], v[146:149], v[178:181], v[134:137]
	v_mfma_f32_16x16x32_bf16 v[134:137], v[150:153], v[190:193], v[134:137]
	v_mfma_f32_16x16x32_bf16 v[118:121], v[146:149], v[194:197], v[118:121]
	v_mfma_f32_16x16x32_bf16 v[118:121], v[150:153], v[198:201], v[118:121]
	v_mfma_f32_16x16x32_bf16 v[102:105], v[146:149], v[202:205], v[102:105]
	v_mfma_f32_16x16x32_bf16 v[102:105], v[150:153], v[206:209], v[102:105]
	v_mfma_f32_16x16x32_bf16 v[70:73], v[146:149], v[210:213], v[70:73]
	v_mfma_f32_16x16x32_bf16 v[70:73], v[150:153], v[220:223], v[70:73]
	v_mfma_f32_16x16x32_bf16 v[130:133], v[154:157], v[178:181], v[130:133]
	v_mfma_f32_16x16x32_bf16 v[130:133], v[158:161], v[190:193], v[130:133]
	v_mfma_f32_16x16x32_bf16 v[114:117], v[154:157], v[194:197], v[114:117]
	v_mfma_f32_16x16x32_bf16 v[114:117], v[158:161], v[198:201], v[114:117]
	v_mfma_f32_16x16x32_bf16 v[98:101], v[154:157], v[202:205], v[98:101]
	v_mfma_f32_16x16x32_bf16 v[98:101], v[158:161], v[206:209], v[98:101]
	v_mfma_f32_16x16x32_bf16 v[66:69], v[154:157], v[210:213], v[66:69]
	v_mfma_f32_16x16x32_bf16 v[66:69], v[158:161], v[220:223], v[66:69]
	s_setprio 0
	s_barrier
; #define PG8_STAGE(bufoff, gbase, voff) do { const char* gb_ = (const char*)(gbase); asm volatile("" : "+s"(gb_)); _Pragma("unroll") for (int _i = 0; _i < 2; ++_i) { unsigned vo_ = (voff)[_i]; asm volatile("" : "+v"(vo_));        \
;         __builtin_amdgcn_global_load_lds((const unsigned*)(gb_ + vo_), (PG8_LAS unsigned*)(lds + (bufoff) + ldsw + _i * 8192), 16, 0, 0); } } while (0)
; #define PG8_LDA(dst, b, h) do { _Pragma("unroll") for (int m = 0; m < 4; ++m) _Pragma("unroll") for (int k = 0; k < 2; ++k) dst[m][k] = *(const PG8_LAS bf16x8*)(lds + PG8_SA(b, h) + aoff + m * 2048 + k * 1024); } while (0)
; #define PG8_LDB(dst, b, h) do { _Pragma("unroll") for (int n = 0; n < 2; ++n) _Pragma("unroll") for (int k = 0; k < 2; ++k) dst[n][k] = *(const PG8_LAS bf16x8*)(lds + PG8_SB(b, h) + boff + n * 2048 + k * 1024); } while (0)
; #define PG8_MMA(ai, bj, At, Bt) do { __builtin_amdgcn_s_setprio(1); _Pragma("unroll") for (int m = 0; m < 4; ++m) _Pragma("unroll") for (int n = 0; n < 2; ++n) _Pragma("unroll") for (int k = 0; k < 2; ++k) \
;         acc[ai][bj][m][n] = __builtin_amdgcn_mfma_f32_16x16x32_bf16(Bt[n][k], At[m][k], acc[ai][bj][m][n], 0, 0, 0); __builtin_amdgcn_s_setprio(0); } while (0)
; #define PG8_WAIT_V(n) asm volatile("s_waitcnt vmcnt(" #n ")" ::: "memory")
; #define PG8_WAIT_L(n) asm volatile("s_waitcnt lgkmcnt(" #n ")" ::: "memory")
; #define PG8_BAR __builtin_amdgcn_s_barrier()
; #define PG8_SCHED __builtin_amdgcn_sched_barrier(0)
; template <class Epi, class Sched, bool ALIGN_EPI = false, bool SP2 = false>
; __device__ __forceinline__ void gemm_phase(PG8_LAS unsigned char* lds, const Gemm g, const Sched& S, const Epi& E) {
;     ...
;             PG8_LDB(B0, 1, 0); PG8_LDB(B1, 1, 1); PG8_SCHED; PG8_LDA(At, 1, 0); PG8_STAGE(PG8_SA(0, 1), a2 + hstep, voffA);
;             PG8_WAIT_V(8); PG8_WAIT_L(0); PG8_BAR; PG8_MMA(0, 0, At, B0); PG8_MMA(0, 1, At, B1); PG8_BAR; PG8_SCHED;
;             PG8_LDA(At, 1, 1); PG8_STAGE(PG8_SB(1, 0), b3, voffB); PG8_STAGE(PG8_SB(1, 1), b3 + hstep, voffB); PG8_STAGE(PG8_SA(1, 0), a3, voffA);
;             PG8_WAIT_V(8); PG8_WAIT_L(0); PG8_BAR; PG8_MMA(1, 0, At, B0); PG8_MMA(1, 1, At, B1); PG8_BAR; PG8_SCHED;
;     ...
;         if constexpr (ALIGN_EPI) { if (wr == 0) PG8_BAR; }
	s_sleep 1
	s_add_u32 s14, s20, 0x80
	s_addc_u32 s15, s21, 0
	s_add_i32 s22, s54, s26
	ds_read_b128 v[178:181], v188 offset:49152
	ds_read_b128 v[190:193], v188 offset:50176
	ds_read_b128 v[194:197], v188 offset:51200
	ds_read_b128 v[198:201], v188 offset:52224
	ds_read_b128 v[202:205], v188 offset:53248
	ds_read_b128 v[206:209], v188 offset:54272
	ds_read_b128 v[210:213], v188 offset:55296
	ds_read_b128 v[220:223], v188 offset:56320
	s_mov_b32 m0, s22
	s_nop 0
	global_load_lds_dwordx4 v162, s[14:15]
	s_add_i32 m0, s22, 0x2000
	s_nop 0
	global_load_lds_dwordx4 v184, s[14:15]
	s_add_u32 s14, s20, 0x80080
	s_addc_u32 s15, s21, 0
	s_add_i32 s20, s55, s26
	s_mov_b32 m0, s20
	s_nop 0
	global_load_lds_dwordx4 v162, s[14:15]
	s_add_i32 m0, s20, 0x2000
	s_nop 0
	global_load_lds_dwordx4 v184, s[14:15]
	s_mov_b32 m0, s38
	s_nop 0
	global_load_lds_dwordx4 v1, s[18:19]
	s_mov_b32 m0, s39
	s_nop 0
	global_load_lds_dwordx4 v164, s[18:19]
	s_waitcnt vmcnt(8)
	s_waitcnt lgkmcnt(0)
	s_barrier
	s_setprio 1
	s_waitcnt lgkmcnt(0)
	v_mfma_f32_16x16x32_bf16 v[62:65], v[82:85], v[178:181], v[62:65]
	v_mfma_f32_16x16x32_bf16 v[62:65], v[86:89], v[190:193], v[62:65]
	v_mfma_f32_16x16x32_bf16 v[46:49], v[82:85], v[194:197], v[46:49]
	v_mfma_f32_16x16x32_bf16 v[46:49], v[86:89], v[198:201], v[46:49]
	v_mfma_f32_16x16x32_bf16 v[30:33], v[82:85], v[202:205], v[30:33]
	v_mfma_f32_16x16x32_bf16 v[30:33], v[86:89], v[206:209], v[30:33]
	v_mfma_f32_16x16x32_bf16 v[14:17], v[82:85], v[210:213], v[14:17]
	v_mfma_f32_16x16x32_bf16 v[14:17], v[86:89], v[220:223], v[14:17]
	v_mfma_f32_16x16x32_bf16 v[58:61], v[90:93], v[178:181], v[58:61]
	v_mfma_f32_16x16x32_bf16 v[58:61], v[94:97], v[190:193], v[58:61]
	v_mfma_f32_16x16x32_bf16 v[42:45], v[90:93], v[194:197], v[42:45]
	v_mfma_f32_16x16x32_bf16 v[42:45], v[94:97], v[198:201], v[42:45]
	v_mfma_f32_16x16x32_bf16 v[26:29], v[90:93], v[202:205], v[26:29]
	v_mfma_f32_16x16x32_bf16 v[26:29], v[94:97], v[206:209], v[26:29]
	v_mfma_f32_16x16x32_bf16 v[10:13], v[90:93], v[210:213], v[10:13]
	v_mfma_f32_16x16x32_bf16 v[10:13], v[94:97], v[220:223], v[10:13]
	s_setprio 0
	s_setprio 1
	v_mfma_f32_16x16x32_bf16 v[54:57], v[146:149], v[178:181], v[54:57]
	v_mfma_f32_16x16x32_bf16 v[54:57], v[150:153], v[190:193], v[54:57]
	v_mfma_f32_16x16x32_bf16 v[38:41], v[146:149], v[194:197], v[38:41]
	v_mfma_f32_16x16x32_bf16 v[38:41], v[150:153], v[198:201], v[38:41]
	v_mfma_f32_16x16x32_bf16 v[22:25], v[146:149], v[202:205], v[22:25]
	v_mfma_f32_16x16x32_bf16 v[22:25], v[150:153], v[206:209], v[22:25]
	v_mfma_f32_16x16x32_bf16 v[6:9], v[146:149], v[210:213], v[6:9]
	v_mfma_f32_16x16x32_bf16 v[6:9], v[150:153], v[220:223], v[6:9]
	v_mfma_f32_16x16x32_bf16 v[50:53], v[154:157], v[178:181], v[50:53]
	v_mfma_f32_16x16x32_bf16 v[50:53], v[158:161], v[190:193], v[50:53]
	v_mfma_f32_16x16x32_bf16 v[34:37], v[154:157], v[194:197], v[34:37]
	v_mfma_f32_16x16x32_bf16 v[34:37], v[158:161], v[198:201], v[34:37]
	v_mfma_f32_16x16x32_bf16 v[18:21], v[154:157], v[202:205], v[18:21]
	v_mfma_f32_16x16x32_bf16 v[18:21], v[158:161], v[206:209], v[18:21]
	v_mfma_f32_16x16x32_bf16 v[2:5], v[154:157], v[210:213], v[2:5]
	v_mfma_f32_16x16x32_bf16 v[2:5], v[158:161], v[220:223], v[2:5]
	s_setprio 0
	s_barrier
	s_sleep 1
	s_add_i32 s53, s53, 2
	s_add_u32 s51, s51, 0x100
	s_addc_u32 s52, s52, 0
	s_cmp_gt_u32 s53, 29
	s_mov_b64 s[14:15], s[16:17]
	s_cbranch_scc0 .LBB0_634
	s_and_b64 vcc, exec, s[2:3]
	s_cbranch_vccz .LBB0_637
	s_barrier

; #define PG8_STAGE(bufoff, gbase, voff) do { const char* gb_ = (const char*)(gbase); asm volatile("" : "+s"(gb_)); _Pragma("unroll") for (int _i = 0; _i < 2; ++_i) { unsigned vo_ = (voff)[_i]; asm volatile("" : "+v"(vo_));        \
;         __builtin_amdgcn_global_load_lds((const unsigned*)(gb_ + vo_), (PG8_LAS unsigned*)(lds + (bufoff) + ldsw + _i * 8192), 16, 0, 0); } } while (0)
; #define PG8_LDA(dst, b, h) do { _Pragma("unroll") for (int m = 0; m < 4; ++m) _Pragma("unroll") for (int k = 0; k < 2; ++k) dst[m][k] = *(const PG8_LAS bf16x8*)(lds + PG8_SA(b, h) + aoff + m * 2048 + k * 1024); } while (0)
; #define PG8_LDB(dst, b, h) do { _Pragma("unroll") for (int n = 0; n < 2; ++n) _Pragma("unroll") for (int k = 0; k < 2; ++k) dst[n][k] = *(const PG8_LAS bf16x8*)(lds + PG8_SB(b, h) + boff + n * 2048 + k * 1024); } while (0)
; #define PG8_MMA(ai, bj, At, Bt) do { __builtin_amdgcn_s_setprio(1); _Pragma("unroll") for (int m = 0; m < 4; ++m) _Pragma("unroll") for (int n = 0; n < 2; ++n) _Pragma("unroll") for (int k = 0; k < 2; ++k) \
;         acc[ai][bj][m][n] = __builtin_amdgcn_mfma_f32_16x16x32_bf16(Bt[n][k], At[m][k], acc[ai][bj][m][n], 0, 0, 0); __builtin_amdgcn_s_setprio(0); } while (0)
; #define PG8_WAIT_V(n) asm volatile("s_waitcnt vmcnt(" #n ")" ::: "memory")
; template <class Epi, class Sched, bool ALIGN_EPI = false, bool SP2 = false>
; __device__ __forceinline__ void gemm_phase(PG8_LAS unsigned char* lds, const Gemm g, const Sched& S, const Epi& E) {
;     ...
;             const bool last = (t == nt - 2);
;             const char* a1 = cA + (size_t)(t + 1) * kstep;
;             const char* a2 = last ? nA : cA + (size_t)(t + 2) * kstep; const char* b2 = last ? nB : cB + (size_t)(t + 2) * kstep;
;             const char* a3 = a2 + kstep; const char* b3 = b2 + kstep;
;             if (last && has_next) S.a_ready(nxt);
;             if constexpr (SP2) {
;             PG8_LDB(B0, 0, 0); PG8_LDB(B1, 0, 1); PG8_SCHED; PG8_LDA(At, 0, 0); PG8_STAGE(PG8_SA(1, 1), a1 + hstep, voffA);
;             PG8_WAIT_V(8); PG8_WAIT_L(0); PG8_BAR; PG8_MMA(0, 0, At, B0); PG8_MMA(0, 1, At, B1); PG8_BAR; PG8_SCHED;
;             PG8_LDA(At, 0, 1); PG8_STAGE(PG8_SB(0, 0), b2, voffB); PG8_STAGE(PG8_SB(0, 1), b2 + hstep, voffB); PG8_STAGE(PG8_SA(0, 0), a2, voffA);
;             PG8_WAIT_V(8); PG8_WAIT_L(0); PG8_BAR; PG8_MMA(1, 0, At, B0); PG8_MMA(1, 1, At, B1); PG8_BAR; PG8_SCHED;
.LBB0_707:
	s_add_u32 s2, s4, 0x100
	s_addc_u32 s3, s5, 0
	s_cmpk_eq_i32 s35, 0x54
	s_cselect_b32 s10, s52, s2
	s_cselect_b32 s11, s53, s3
	s_cselect_b32 s8, s42, s31
	s_cselect_b32 s9, s43, s34
	s_add_u32 s6, s10, 0x80
	s_addc_u32 s7, s11, 0
	s_add_i32 s38, 0, 0x10000
	s_add_i32 s39, 0, 0x14000
	ds_read_b128 v[34:37], v244
	ds_read_b128 v[38:41], v244 offset:1024
	ds_read_b128 v[98:101], v244 offset:2048
	ds_read_b128 v[102:105], v244 offset:3072
	ds_read_b128 v[146:149], v244 offset:16384
	ds_read_b128 v[150:153], v244 offset:17408
	ds_read_b128 v[154:157], v244 offset:18432
	ds_read_b128 v[158:161], v244 offset:19456
	s_add_u32 s4, s4, 0x160080
	s_addc_u32 s5, s5, 0
	ds_read_b128 v[178:181], v194
	ds_read_b128 v[182:185], v194 offset:1024
	ds_read_b128 v[186:189], v194 offset:2048
	ds_read_b128 v[196:199], v194 offset:3072
	ds_read_b128 v[200:203], v194 offset:4096
	ds_read_b128 v[204:207], v194 offset:5120
	ds_read_b128 v[208:211], v194 offset:6144
	ds_read_b128 v[212:215], v194 offset:7168
	s_add_i32 m0, s16, 0xc000
	s_nop 0
	global_load_lds_dwordx4 v1, s[4:5]
	s_add_i32 m0, s16, 0xe000
	s_nop 0
	global_load_lds_dwordx4 v164, s[4:5]
	s_waitcnt vmcnt(8)
	s_waitcnt lgkmcnt(0)
	s_barrier
	s_setprio 1
	s_waitcnt lgkmcnt(0)
	v_mfma_f32_16x16x32_bf16 v[142:145], v[34:37], v[178:181], v[142:145]
	v_mfma_f32_16x16x32_bf16 v[142:145], v[38:41], v[182:185], v[142:145]
	v_mfma_f32_16x16x32_bf16 v[134:137], v[34:37], v[186:189], v[134:137]
	v_mfma_f32_16x16x32_bf16 v[134:137], v[38:41], v[196:199], v[134:137]
	v_mfma_f32_16x16x32_bf16 v[126:129], v[34:37], v[200:203], v[126:129]
	v_mfma_f32_16x16x32_bf16 v[126:129], v[38:41], v[204:207], v[126:129]
	v_mfma_f32_16x16x32_bf16 v[118:121], v[34:37], v[208:211], v[118:121]
	v_mfma_f32_16x16x32_bf16 v[118:121], v[38:41], v[212:215], v[118:121]
	v_mfma_f32_16x16x32_bf16 v[138:141], v[98:101], v[178:181], v[138:141]
	v_mfma_f32_16x16x32_bf16 v[138:141], v[102:105], v[182:185], v[138:141]
	v_mfma_f32_16x16x32_bf16 v[130:133], v[98:101], v[186:189], v[130:133]
	v_mfma_f32_16x16x32_bf16 v[130:133], v[102:105], v[196:199], v[130:133]
	v_mfma_f32_16x16x32_bf16 v[122:125], v[98:101], v[200:203], v[122:125]
	v_mfma_f32_16x16x32_bf16 v[122:125], v[102:105], v[204:207], v[122:125]
	v_mfma_f32_16x16x32_bf16 v[114:117], v[98:101], v[208:211], v[114:117]
	v_mfma_f32_16x16x32_bf16 v[114:117], v[102:105], v[212:215], v[114:117]
	s_setprio 0
	s_setprio 1
	v_mfma_f32_16x16x32_bf16 v[70:73], v[146:149], v[178:181], v[70:73]
	v_mfma_f32_16x16x32_bf16 v[70:73], v[150:153], v[182:185], v[70:73]
	v_mfma_f32_16x16x32_bf16 v[62:65], v[146:149], v[186:189], v[62:65]
	v_mfma_f32_16x16x32_bf16 v[62:65], v[150:153], v[196:199], v[62:65]
	v_mfma_f32_16x16x32_bf16 v[54:57], v[146:149], v[200:203], v[54:57]
	v_mfma_f32_16x16x32_bf16 v[54:57], v[150:153], v[204:207], v[54:57]
	v_mfma_f32_16x16x32_bf16 v[46:49], v[146:149], v[208:211], v[46:49]
	v_mfma_f32_16x16x32_bf16 v[46:49], v[150:153], v[212:215], v[46:49]
	v_mfma_f32_16x16x32_bf16 v[66:69], v[154:157], v[178:181], v[66:69]
	v_mfma_f32_16x16x32_bf16 v[66:69], v[158:161], v[182:185], v[66:69]
	v_mfma_f32_16x16x32_bf16 v[58:61], v[154:157], v[186:189], v[58:61]
	v_mfma_f32_16x16x32_bf16 v[58:61], v[158:161], v[196:199], v[58:61]
	v_mfma_f32_16x16x32_bf16 v[50:53], v[154:157], v[200:203], v[50:53]
	v_mfma_f32_16x16x32_bf16 v[50:53], v[158:161], v[204:207], v[50:53]
	v_mfma_f32_16x16x32_bf16 v[42:45], v[154:157], v[208:211], v[42:45]
	v_mfma_f32_16x16x32_bf16 v[42:45], v[158:161], v[212:215], v[42:45]
	s_setprio 0
	s_barrier
	s_sleep 1
	s_mov_b64 s[4:5], s[8:9]
	s_add_i32 s38, s38, s15
	ds_read_b128 v[178:181], v194 offset:16384
	ds_read_b128 v[182:185], v194 offset:17408
	ds_read_b128 v[186:189], v194 offset:18432
	ds_read_b128 v[196:199], v194 offset:19456
	ds_read_b128 v[200:203], v194 offset:20480
	ds_read_b128 v[204:207], v194 offset:21504
	ds_read_b128 v[208:211], v194 offset:22528
	ds_read_b128 v[212:215], v194 offset:23552
	s_mov_b32 m0, s38
	s_nop 0
	global_load_lds_dwordx4 v162, s[4:5]
	s_add_i32 m0, s38, 0x2000
	s_nop 0
	global_load_lds_dwordx4 v190, s[4:5]
	s_add_u32 s4, s8, 0x160000
	s_addc_u32 s5, s9, 0
	s_add_i32 s38, s39, s15
	s_mov_b32 m0, s38
	s_nop 0
	global_load_lds_dwordx4 v162, s[4:5]
	s_add_i32 m0, s38, 0x2000
	s_nop 0
	global_load_lds_dwordx4 v190, s[4:5]
	s_mov_b64 s[4:5], s[10:11]
	s_mov_b32 m0, s16
	s_nop 0
	global_load_lds_dwordx4 v1, s[4:5]
	s_mov_b32 m0, s17
	s_nop 0
	global_load_lds_dwordx4 v164, s[4:5]
	s_waitcnt vmcnt(8)
	s_waitcnt lgkmcnt(0)
	s_barrier
; #define PG8_STAGE(bufoff, gbase, voff) do { const char* gb_ = (const char*)(gbase); asm volatile("" : "+s"(gb_)); _Pragma("unroll") for (int _i = 0; _i < 2; ++_i) { unsigned vo_ = (voff)[_i]; asm volatile("" : "+v"(vo_));        \
;         __builtin_amdgcn_global_load_lds((const unsigned*)(gb_ + vo_), (PG8_LAS unsigned*)(lds + (bufoff) + ldsw + _i * 8192), 16, 0, 0); } } while (0)
; #define PG8_LDA(dst, b, h) do { _Pragma("unroll") for (int m = 0; m < 4; ++m) _Pragma("unroll") for (int k = 0; k < 2; ++k) dst[m][k] = *(const PG8_LAS bf16x8*)(lds + PG8_SA(b, h) + aoff + m * 2048 + k * 1024); } while (0)
; #define PG8_LDB(dst, b, h) do { _Pragma("unroll") for (int n = 0; n < 2; ++n) _Pragma("unroll") for (int k = 0; k < 2; ++k) dst[n][k] = *(const PG8_LAS bf16x8*)(lds + PG8_SB(b, h) + boff + n * 2048 + k * 1024); } while (0)
; #define PG8_MMA(ai, bj, At, Bt) do { __builtin_amdgcn_s_setprio(1); _Pragma("unroll") for (int m = 0; m < 4; ++m) _Pragma("unroll") for (int n = 0; n < 2; ++n) _Pragma("unroll") for (int k = 0; k < 2; ++k) \
;         acc[ai][bj][m][n] = __builtin_amdgcn_mfma_f32_16x16x32_bf16(Bt[n][k], At[m][k], acc[ai][bj][m][n], 0, 0, 0); __builtin_amdgcn_s_setprio(0); } while (0)
; #define PG8_WAIT_V(n) asm volatile("s_waitcnt vmcnt(" #n ")" ::: "memory")
; #define PG8_WAIT_L(n) asm volatile("s_waitcnt lgkmcnt(" #n ")" ::: "memory")
; #define PG8_BAR __builtin_amdgcn_s_barrier()
; #define PG8_SCHED __builtin_amdgcn_sched_barrier(0)
; template <class Epi, class Sched, bool ALIGN_EPI = false, bool SP2 = false>
; __device__ __forceinline__ void gemm_phase(PG8_LAS unsigned char* lds, const Gemm g, const Sched& S, const Epi& E) {
;     ...
;             PG8_WAIT_V(8); PG8_WAIT_L(0); PG8_BAR; PG8_MMA(1, 0, At, B0); PG8_MMA(1, 1, At, B1); PG8_BAR; PG8_SCHED;
;             PG8_LDB(B0, 1, 0); PG8_LDB(B1, 1, 1); PG8_SCHED; PG8_LDA(At, 1, 0); PG8_STAGE(PG8_SA(0, 1), a2 + hstep, voffA);
;             PG8_WAIT_V(8); PG8_WAIT_L(0); PG8_BAR; PG8_MMA(0, 0, At, B0); PG8_MMA(0, 1, At, B1); PG8_BAR; PG8_SCHED;
	s_setprio 1
	s_waitcnt lgkmcnt(0)
	v_mfma_f32_16x16x32_bf16 v[110:113], v[34:37], v[178:181], v[110:113]
	v_mfma_f32_16x16x32_bf16 v[110:113], v[38:41], v[182:185], v[110:113]
	v_mfma_f32_16x16x32_bf16 v[94:97], v[34:37], v[186:189], v[94:97]
	v_mfma_f32_16x16x32_bf16 v[94:97], v[38:41], v[196:199], v[94:97]
	v_mfma_f32_16x16x32_bf16 v[86:89], v[34:37], v[200:203], v[86:89]
	v_mfma_f32_16x16x32_bf16 v[86:89], v[38:41], v[204:207], v[86:89]
	v_mfma_f32_16x16x32_bf16 v[34:37], v[34:37], v[208:211], v[78:81]
	v_mfma_f32_16x16x32_bf16 v[34:37], v[38:41], v[212:215], v[34:37]
	v_mfma_f32_16x16x32_bf16 v[106:109], v[98:101], v[178:181], v[106:109]
	v_mfma_f32_16x16x32_bf16 v[106:109], v[102:105], v[182:185], v[106:109]
	v_mfma_f32_16x16x32_bf16 v[90:93], v[98:101], v[186:189], v[90:93]
	v_mfma_f32_16x16x32_bf16 v[90:93], v[102:105], v[196:199], v[90:93]
	v_mfma_f32_16x16x32_bf16 v[82:85], v[98:101], v[200:203], v[82:85]
	v_mfma_f32_16x16x32_bf16 v[82:85], v[102:105], v[204:207], v[82:85]
	v_mfma_f32_16x16x32_bf16 v[38:41], v[98:101], v[208:211], v[74:77]
	v_mfma_f32_16x16x32_bf16 v[38:41], v[102:105], v[212:215], v[38:41]
	s_setprio 0
	s_setprio 1
	v_mfma_f32_16x16x32_bf16 v[30:33], v[146:149], v[178:181], v[30:33]
	v_mfma_f32_16x16x32_bf16 v[30:33], v[150:153], v[182:185], v[30:33]
	v_mfma_f32_16x16x32_bf16 v[22:25], v[146:149], v[186:189], v[22:25]
	v_mfma_f32_16x16x32_bf16 v[22:25], v[150:153], v[196:199], v[22:25]
	v_mfma_f32_16x16x32_bf16 v[14:17], v[146:149], v[200:203], v[14:17]
	v_mfma_f32_16x16x32_bf16 v[14:17], v[150:153], v[204:207], v[14:17]
	v_mfma_f32_16x16x32_bf16 v[6:9], v[146:149], v[208:211], v[6:9]
	v_mfma_f32_16x16x32_bf16 v[6:9], v[150:153], v[212:215], v[6:9]
	v_mfma_f32_16x16x32_bf16 v[26:29], v[154:157], v[178:181], v[26:29]
	v_mfma_f32_16x16x32_bf16 v[26:29], v[158:161], v[182:185], v[26:29]
	v_mfma_f32_16x16x32_bf16 v[18:21], v[154:157], v[186:189], v[18:21]
	v_mfma_f32_16x16x32_bf16 v[18:21], v[158:161], v[196:199], v[18:21]
	v_mfma_f32_16x16x32_bf16 v[10:13], v[154:157], v[200:203], v[10:13]
	v_mfma_f32_16x16x32_bf16 v[10:13], v[158:161], v[204:207], v[10:13]
	v_mfma_f32_16x16x32_bf16 v[2:5], v[154:157], v[208:211], v[2:5]
	v_mfma_f32_16x16x32_bf16 v[2:5], v[158:161], v[212:215], v[2:5]
	s_setprio 0
	s_barrier
	s_sleep 1
	s_add_i32 s38, 0, 0x18000
	s_add_i32 s39, 0, 0x1c000
	ds_read_b128 v[74:77], v244 offset:32768
	ds_read_b128 v[78:81], v244 offset:33792
	ds_read_b128 v[98:101], v244 offset:34816
	ds_read_b128 v[102:105], v244 offset:35840
	ds_read_b128 v[146:149], v244 offset:49152
	ds_read_b128 v[150:153], v244 offset:50176
	ds_read_b128 v[154:157], v244 offset:51200
	ds_read_b128 v[158:161], v244 offset:52224
	s_add_u32 s4, s10, 0x160000
	s_addc_u32 s5, s11, 0
	s_mov_b32 m0, s18
	ds_read_b128 v[178:181], v194 offset:32768
	ds_read_b128 v[182:185], v194 offset:33792
	ds_read_b128 v[186:189], v194 offset:34816
	ds_read_b128 v[196:199], v194 offset:35840
	ds_read_b128 v[200:203], v194 offset:36864
	ds_read_b128 v[204:207], v194 offset:37888
	ds_read_b128 v[208:211], v194 offset:38912
	ds_read_b128 v[212:215], v194 offset:39936
	s_nop 0
	global_load_lds_dwordx4 v1, s[4:5]
	s_mov_b32 m0, s19
	s_nop 0
	global_load_lds_dwordx4 v164, s[4:5]
	s_waitcnt vmcnt(8)
	s_waitcnt lgkmcnt(0)
	s_barrier
	s_setprio 1
	s_waitcnt lgkmcnt(0)
	v_mfma_f32_16x16x32_bf16 v[142:145], v[74:77], v[178:181], v[142:145]
	v_mfma_f32_16x16x32_bf16 v[142:145], v[78:81], v[182:185], v[142:145]
	v_mfma_f32_16x16x32_bf16 v[134:137], v[74:77], v[186:189], v[134:137]
	v_mfma_f32_16x16x32_bf16 v[134:137], v[78:81], v[196:199], v[134:137]
	v_mfma_f32_16x16x32_bf16 v[126:129], v[74:77], v[200:203], v[126:129]
	v_mfma_f32_16x16x32_bf16 v[126:129], v[78:81], v[204:207], v[126:129]
	v_mfma_f32_16x16x32_bf16 v[118:121], v[74:77], v[208:211], v[118:121]
	v_mfma_f32_16x16x32_bf16 v[118:121], v[78:81], v[212:215], v[118:121]
	v_mfma_f32_16x16x32_bf16 v[138:141], v[98:101], v[178:181], v[138:141]
	v_mfma_f32_16x16x32_bf16 v[138:141], v[102:105], v[182:185], v[138:141]
	v_mfma_f32_16x16x32_bf16 v[130:133], v[98:101], v[186:189], v[130:133]
	v_mfma_f32_16x16x32_bf16 v[130:133], v[102:105], v[196:199], v[130:133]
	v_mfma_f32_16x16x32_bf16 v[122:125], v[98:101], v[200:203], v[122:125]
	v_mfma_f32_16x16x32_bf16 v[122:125], v[102:105], v[204:207], v[122:125]
	v_mfma_f32_16x16x32_bf16 v[114:117], v[98:101], v[208:211], v[114:117]
	v_mfma_f32_16x16x32_bf16 v[114:117], v[102:105], v[212:215], v[114:117]
	s_setprio 0
	s_setprio 1
	v_mfma_f32_16x16x32_bf16 v[70:73], v[146:149], v[178:181], v[70:73]
	v_mfma_f32_16x16x32_bf16 v[70:73], v[150:153], v[182:185], v[70:73]
	v_mfma_f32_16x16x32_bf16 v[62:65], v[146:149], v[186:189], v[62:65]
	v_mfma_f32_16x16x32_bf16 v[62:65], v[150:153], v[196:199], v[62:65]
	v_mfma_f32_16x16x32_bf16 v[54:57], v[146:149], v[200:203], v[54:57]
	v_mfma_f32_16x16x32_bf16 v[54:57], v[150:153], v[204:207], v[54:57]
	v_mfma_f32_16x16x32_bf16 v[46:49], v[146:149], v[208:211], v[46:49]
	v_mfma_f32_16x16x32_bf16 v[46:49], v[150:153], v[212:215], v[46:49]
	v_mfma_f32_16x16x32_bf16 v[66:69], v[154:157], v[178:181], v[66:69]
	v_mfma_f32_16x16x32_bf16 v[66:69], v[158:161], v[182:185], v[66:69]
	v_mfma_f32_16x16x32_bf16 v[58:61], v[154:157], v[186:189], v[58:61]
	v_mfma_f32_16x16x32_bf16 v[58:61], v[158:161], v[196:199], v[58:61]
	v_mfma_f32_16x16x32_bf16 v[50:53], v[154:157], v[200:203], v[50:53]
	v_mfma_f32_16x16x32_bf16 v[50:53], v[158:161], v[204:207], v[50:53]
	v_mfma_f32_16x16x32_bf16 v[42:45], v[154:157], v[208:211], v[42:45]
	v_mfma_f32_16x16x32_bf16 v[42:45], v[158:161], v[212:215], v[42:45]
	s_setprio 0
	s_barrier
; #define PG8_STAGE(bufoff, gbase, voff) do { const char* gb_ = (const char*)(gbase); asm volatile("" : "+s"(gb_)); _Pragma("unroll") for (int _i = 0; _i < 2; ++_i) { unsigned vo_ = (voff)[_i]; asm volatile("" : "+v"(vo_));        \
;         __builtin_amdgcn_global_load_lds((const unsigned*)(gb_ + vo_), (PG8_LAS unsigned*)(lds + (bufoff) + ldsw + _i * 8192), 16, 0, 0); } } while (0)
; #define PG8_LDA(dst, b, h) do { _Pragma("unroll") for (int m = 0; m < 4; ++m) _Pragma("unroll") for (int k = 0; k < 2; ++k) dst[m][k] = *(const PG8_LAS bf16x8*)(lds + PG8_SA(b, h) + aoff + m * 2048 + k * 1024); } while (0)
; #define PG8_WAIT_V(n) asm volatile("s_waitcnt vmcnt(" #n ")" ::: "memory")
; #define PG8_WAIT_L(n) asm volatile("s_waitcnt lgkmcnt(" #n ")" ::: "memory")
; #define PG8_BAR __builtin_amdgcn_s_barrier()
; #define PG8_SCHED __builtin_amdgcn_sched_barrier(0)
;     __device__ __forceinline__ void operator()(const f32x4 (&acc)[2][2][4][2], const Unit& u, int wr, int wc, int fr, int fq) const {
;         const int row0 = u.pm * BM + wr * 64 + fr, col0 = u.pn * BM + wc * 32 + 8 * fq, b = (u.pm * BM) / rows_per_batch;
;         const float* g = gate + (size_t)b * gate_bstride + col0;
;         float ssq[2][4];
; #pragma unroll
;         for (int ai = 0; ai < 2; ++ai)
; #pragma unroll
;             for (int m = 0; m < 4; ++m) ssq[ai][m] = 0.f;
;         f32x4 gv[2][2], Gv[2][2];
; #pragma unroll
;         for (int bj = 0; bj < 2; ++bj) { gv[bj][0] = *(const f32x4*)(g + bj * HALF); gv[bj][1] = *(const f32x4*)(g + bj * HALF + 4); Gv[bj][0] = (f32x4){0.f, 0.f, 0.f, 0.f}; Gv[bj][1] = (f32x4){0.f, 0.f, 0.f, 0.f};
;             if (Hn) { const float* sc = scnext + (size_t)b * gate_bstride + col0 + bj * HALF;
;                 Gv[bj][0] = *(const f32x4*)(gnext + col0 + bj * HALF) * (1.0f + *(const f32x4*)(sc)); Gv[bj][1] = *(const f32x4*)(gnext + col0 + bj * HALF + 4) * (1.0f + *(const f32x4*)(sc + 4)); } }
; template <class Epi, class Sched, bool ALIGN_EPI = false, bool SP2 = false>
; __device__ __forceinline__ void gemm_phase(PG8_LAS unsigned char* lds, const Gemm g, const Sched& S, const Epi& E) {
;     ...
;             PG8_LDA(At, 1, 1); PG8_STAGE(PG8_SB(1, 0), b3, voffB); PG8_STAGE(PG8_SB(1, 1), b3 + hstep, voffB); PG8_STAGE(PG8_SA(1, 0), a3, voffA);
;             PG8_WAIT_V(8); PG8_WAIT_L(0); PG8_BAR; PG8_MMA(1, 0, At, B0); PG8_MMA(1, 1, At, B1); PG8_BAR; PG8_SCHED;
	s_sleep 1
	s_add_u32 s4, s8, 0x80
	s_addc_u32 s5, s9, 0
	s_add_i32 s10, s38, s15
	ds_read_b128 v[178:181], v194 offset:49152
	ds_read_b128 v[182:185], v194 offset:50176
	ds_read_b128 v[186:189], v194 offset:51200
	ds_read_b128 v[196:199], v194 offset:52224
	ds_read_b128 v[200:203], v194 offset:53248
	ds_read_b128 v[204:207], v194 offset:54272
	ds_read_b128 v[208:211], v194 offset:55296
	ds_read_b128 v[212:215], v194 offset:56320
	s_mov_b32 m0, s10
	s_nop 0
	global_load_lds_dwordx4 v162, s[4:5]
	s_add_i32 m0, s10, 0x2000
	s_nop 0
	global_load_lds_dwordx4 v190, s[4:5]
	s_add_u32 s4, s8, 0x160080
	s_addc_u32 s5, s9, 0
	s_add_i32 s8, s39, s15
	s_mov_b32 m0, s8
	s_nop 0
	global_load_lds_dwordx4 v162, s[4:5]
	s_add_i32 m0, s8, 0x2000
	s_nop 0
	global_load_lds_dwordx4 v190, s[4:5]
	s_mov_b32 m0, s24
	s_nop 0
	global_load_lds_dwordx4 v1, s[6:7]
	s_mov_b32 m0, s25
	s_nop 0
	global_load_lds_dwordx4 v164, s[6:7]
	s_waitcnt vmcnt(8)
	s_waitcnt lgkmcnt(0)
	s_barrier
	s_setprio 1
	s_waitcnt lgkmcnt(0)
	v_mfma_f32_16x16x32_bf16 v[110:113], v[74:77], v[178:181], v[110:113]
	v_mfma_f32_16x16x32_bf16 v[110:113], v[78:81], v[182:185], v[110:113]
	v_mfma_f32_16x16x32_bf16 v[94:97], v[74:77], v[186:189], v[94:97]
	v_mfma_f32_16x16x32_bf16 v[94:97], v[78:81], v[196:199], v[94:97]
	v_mfma_f32_16x16x32_bf16 v[86:89], v[74:77], v[200:203], v[86:89]
	v_mfma_f32_16x16x32_bf16 v[86:89], v[78:81], v[204:207], v[86:89]
	v_mfma_f32_16x16x32_bf16 v[34:37], v[74:77], v[208:211], v[34:37]
	v_mfma_f32_16x16x32_bf16 v[78:81], v[78:81], v[212:215], v[34:37]
	v_mfma_f32_16x16x32_bf16 v[106:109], v[98:101], v[178:181], v[106:109]
	v_mfma_f32_16x16x32_bf16 v[106:109], v[102:105], v[182:185], v[106:109]
	v_mfma_f32_16x16x32_bf16 v[90:93], v[98:101], v[186:189], v[90:93]
	v_mfma_f32_16x16x32_bf16 v[90:93], v[102:105], v[196:199], v[90:93]
	v_mfma_f32_16x16x32_bf16 v[82:85], v[98:101], v[200:203], v[82:85]
	v_mfma_f32_16x16x32_bf16 v[82:85], v[102:105], v[204:207], v[82:85]
	v_mfma_f32_16x16x32_bf16 v[34:37], v[98:101], v[208:211], v[38:41]
	v_mfma_f32_16x16x32_bf16 v[74:77], v[102:105], v[212:215], v[34:37]
	s_setprio 0
	s_setprio 1
	v_mfma_f32_16x16x32_bf16 v[30:33], v[146:149], v[178:181], v[30:33]
	v_mfma_f32_16x16x32_bf16 v[30:33], v[150:153], v[182:185], v[30:33]
	v_mfma_f32_16x16x32_bf16 v[22:25], v[146:149], v[186:189], v[22:25]
	v_mfma_f32_16x16x32_bf16 v[22:25], v[150:153], v[196:199], v[22:25]
	v_mfma_f32_16x16x32_bf16 v[14:17], v[146:149], v[200:203], v[14:17]
	v_mfma_f32_16x16x32_bf16 v[14:17], v[150:153], v[204:207], v[14:17]
	v_mfma_f32_16x16x32_bf16 v[6:9], v[146:149], v[208:211], v[6:9]
	v_mfma_f32_16x16x32_bf16 v[6:9], v[150:153], v[212:215], v[6:9]
	v_mfma_f32_16x16x32_bf16 v[26:29], v[154:157], v[178:181], v[26:29]
	v_mfma_f32_16x16x32_bf16 v[26:29], v[158:161], v[182:185], v[26:29]
	v_mfma_f32_16x16x32_bf16 v[18:21], v[154:157], v[186:189], v[18:21]
	v_mfma_f32_16x16x32_bf16 v[18:21], v[158:161], v[196:199], v[18:21]
	v_mfma_f32_16x16x32_bf16 v[10:13], v[154:157], v[200:203], v[10:13]
	v_mfma_f32_16x16x32_bf16 v[10:13], v[158:161], v[204:207], v[10:13]
	v_mfma_f32_16x16x32_bf16 v[2:5], v[154:157], v[208:211], v[2:5]
	v_mfma_f32_16x16x32_bf16 v[2:5], v[158:161], v[212:215], v[2:5]
	s_setprio 0
	s_barrier
	s_sleep 1
	s_add_i32 s35, s35, 2
	s_add_u32 s31, s31, 0x100
	s_addc_u32 s34, s34, 0
	s_cmpk_gt_u32 s35, 0x55
	s_mov_b64 s[4:5], s[2:3]
	s_cbranch_scc0 .LBB0_707
	s_ashr_i32 s2, s29, 31
	s_lshr_b32 s2, s2, 27
	s_add_i32 s2, s29, s2
	s_ashr_i32 s2, s2, 5
	v_lshl_or_b32 v156, s30, 8, v193
	s_mul_i32 s5, s2, 0xc000
	v_ashrrev_i32_e32 v157, 31, v156
	s_mul_hi_i32 s4, s2, 0xc000
	s_add_u32 s2, s20, s5
	s_addc_u32 s3, s21, s4
	v_lshlrev_b64 v[34:35], 2, v[156:157]
	v_lshl_add_u64 v[38:39], s[2:3], 0, v[34:35]
	global_load_dwordx4 v[98:101], v[38:39], off offset:16
	global_load_dwordx4 v[102:105], v[38:39], off
	s_add_u32 s2, s22, s5
	s_addc_u32 s3, s23, s4
	v_lshl_add_u64 v[148:149], s[2:3], 0, v[34:35]
	v_lshl_add_u64 v[146:147], s[48:49], 0, v[34:35]
	v_mov_b32_e32 v158, 0
	v_cndmask_b32_e64 v34, 0, 1, s[46:47]
	v_cmp_ne_u32_e64 s[2:3], 1, v34
	s_andn2_b64 vcc, exec, s[46:47]
	v_mov_b32_e32 v159, v158
	v_mov_b32_e32 v160, v158
	v_mov_b32_e32 v161, v158
	v_mov_b32_e32 v178, v158
	v_mov_b32_e32 v179, v158
	v_mov_b32_e32 v180, v158
	v_mov_b32_e32 v181, v158
	s_cbranch_vccnz .LBB0_710
	global_load_dwordx4 v[34:37], v[148:149], off
	global_load_dwordx4 v[150:153], v[148:149], off offset:16
	global_load_dwordx4 v[158:161], v[146:147], off
	global_load_dwordx4 v[178:181], v[146:147], off offset:16
	s_waitcnt vmcnt(0)
	v_pk_add_f32 v[36:37], v[36:37], 1.0 op_sel_hi:[1,0]
	v_pk_add_f32 v[34:35], v[34:35], 1.0 op_sel_hi:[1,0]
	v_pk_add_f32 v[40:41], v[152:153], 1.0 op_sel_hi:[1,0]
	v_pk_add_f32 v[150:151], v[150:151], 1.0 op_sel_hi:[1,0]
	v_pk_mul_f32 v[160:161], v[160:161], v[36:37]
	v_pk_mul_f32 v[158:159], v[158:159], v[34:35]
	v_pk_mul_f32 v[180:181], v[180:181], v[40:41]
	v_pk_mul_f32 v[178:179], v[178:179], v[150:151]
